# write-through sc1 kept only on the w_in projection stores; P0 / LRU pass stores back to plain; on top of v28
# baseline (speedup 1.0000x reference)
; #define LAS __attribute__((address_space(3)))
; __device__ __forceinline__ unsigned cvt_pk_bf16(float lo, float hi) { unsigned r; asm volatile("v_cvt_pk_bf16_f32 %0, %1, %2" : "=v"(r) : "v"(lo), "v"(hi)); return r; }
; __device__ __forceinline__ float bflo(unsigned w) { return __uint_as_float(w << 16); }
; __device__ __forceinline__ float bfhi(unsigned w) { return __uint_as_float(w & 0xffff0000u); }
; template <int PASS> __device__ __forceinline__ void lru_wave_item(LAS unsigned char* lds, LAS unsigned char* vw, int b, int c, int h, const MixP& p, int lane, float (&Hrun)[8], bool cont) {
;     ...
;     for (int st = 0; st < CT / 16; ++st) {
;         const int s0 = c * CT + 16 * st;
;         u32x4 ur[7];
;         {
;             const int sb = s0 + 4 * fq - 3;
; #pragma unroll
;             for (int r = 0; r < 7; ++r) ur[r] = *(const u32x4*)(ub + (size_t)max(sb + r, 0) * P1W);
;         }
;         if (s0 == 0 && fq == 0) {
; #pragma unroll
;             for (int r = 0; r < 3; ++r) ur[r] = (u32x4){0u, 0u, 0u, 0u};
;         }
; #pragma unroll
;         for (int jj = 0; jj < 4; ++jj) {
;             f32x2 o[4] = {bv[0], bv[1], bv[2], bv[3]};
; #pragma unroll
;             for (int k = 0; k < 4; ++k) { const u32x4 uk = ur[jj + k];
;                 o[0] = wv[k][0] * (f32x2){bflo(uk.x), bfhi(uk.x)} + o[0]; o[1] = wv[k][1] * (f32x2){bflo(uk.y), bfhi(uk.y)} + o[1];
;                 o[2] = wv[k][2] * (f32x2){bflo(uk.z), bfhi(uk.z)} + o[2]; o[3] = wv[k][3] * (f32x2){bflo(uk.w), bfhi(uk.w)} + o[3]; }
;             { u32x4 w; w.x = cvt_pk_bf16(o[0].x, o[0].y); w.y = cvt_pk_bf16(o[1].x, o[1].y); w.z = cvt_pk_bf16(o[2].x, o[2].y); w.w = cvt_pk_bf16(o[3].x, o[3].y);
;               *(LAS u32x4*)(vw + (4 * fq + jj) * WROW + cg * 16) = w; }
;         }
.LBB0_668:
	s_or_b32 s2, s19, s13
	v_add_u32_e32 v74, s2, v230
	v_cndmask_b32_e64 v50, 0, 1, s[28:29]
	v_max_i32_e32 v54, -1, v74
	v_cmp_ne_u32_e32 vcc, 1, v50
	v_max_i32_e32 v50, 0, v74
	v_add_u32_e32 v54, 1, v54
	v_or_b32_e32 v58, 2, v74
	v_mad_u64_u32 v[50:51], s[20:21], v50, s82, v[196:197]
	v_mad_u64_u32 v[54:55], s[20:21], v54, s82, v[196:197]
	v_max_i32_e32 v58, 0, v58
	global_load_dwordx4 v[50:53], v[50:51], off offset:1024
	v_mad_u64_u32 v[58:59], s[20:21], v58, s82, v[196:197]
	global_load_dwordx4 v[54:57], v[54:55], off offset:1024
	v_or_b32_e32 v62, s2, v229
	global_load_dwordx4 v[58:61], v[58:59], off offset:1024
	v_max_i32_e32 v62, 0, v62
	v_mad_u64_u32 v[62:63], s[20:21], v62, s82, v[196:197]
	global_load_dwordx4 v[62:65], v[62:63], off offset:1024
	v_max_i32_e32 v66, -4, v74
	v_add_u32_e32 v66, 4, v66
	v_mad_u64_u32 v[66:67], s[20:21], v66, s82, v[196:197]
	global_load_dwordx4 v[66:69], v[66:67], off offset:1024
	v_max_i32_e32 v70, -5, v74
	v_add_u32_e32 v70, 5, v70
	v_mad_u64_u32 v[70:71], s[20:21], v70, s82, v[196:197]
	global_load_dwordx4 v[70:73], v[70:71], off offset:1024
	v_max_i32_e32 v74, -6, v74
	v_add_u32_e32 v74, 6, v74
	v_mad_u64_u32 v[74:75], s[20:21], v74, s82, v[196:197]
	global_load_dwordx4 v[74:77], v[74:75], off offset:1024
	s_add_i32 s100, s2, 16
	v_add_u32_e32 v92, s100, v230
	v_max_i32_e32 v93, 0, v92
	v_mad_u64_u32 v[94:95], s[98:99], v93, s82, v[196:197]
	global_load_dword v206, v[94:95], off offset:1024
	v_add_u32_e32 v93, 1, v92
	v_max_i32_e32 v93, 0, v93
	v_mad_u64_u32 v[94:95], s[98:99], v93, s82, v[196:197]
	global_load_dword v206, v[94:95], off offset:1024
	v_add_u32_e32 v93, 2, v92
	v_max_i32_e32 v93, 0, v93
	v_mad_u64_u32 v[94:95], s[98:99], v93, s82, v[196:197]
	global_load_dword v206, v[94:95], off offset:1024
	v_add_u32_e32 v93, 3, v92
	v_max_i32_e32 v93, 0, v93
	v_mad_u64_u32 v[94:95], s[98:99], v93, s82, v[196:197]
	global_load_dword v206, v[94:95], off offset:1024
	v_add_u32_e32 v93, 4, v92
	v_max_i32_e32 v93, 0, v93
	v_mad_u64_u32 v[94:95], s[98:99], v93, s82, v[196:197]
	global_load_dword v206, v[94:95], off offset:1024
	v_add_u32_e32 v93, 5, v92
	v_max_i32_e32 v93, 0, v93
	v_mad_u64_u32 v[94:95], s[98:99], v93, s82, v[196:197]
	global_load_dword v206, v[94:95], off offset:1024
	v_add_u32_e32 v93, 6, v92
	v_max_i32_e32 v93, 0, v93
	v_mad_u64_u32 v[94:95], s[98:99], v93, s82, v[196:197]
	global_load_dword v206, v[94:95], off offset:1024
	s_cmp_eq_u32 s2, 0
	s_cselect_b64 s[16:17], -1, 0
	s_and_b64 s[16:17], s[16:17], s[4:5]
	v_add_u32_e32 v138, v234, v231
	s_mov_b32 s19, 16
	s_mov_b64 s[28:29], 0
	s_and_b64 vcc, exec, vcc
	s_waitcnt vmcnt(12)
	v_cndmask_b32_e64 v81, v57, 0, s[16:17]
	v_cndmask_b32_e64 v57, v53, 0, s[16:17]
	v_cndmask_b32_e64 v53, v51, 0, s[16:17]
	v_cndmask_b32_e64 v51, v50, 0, s[16:17]
	s_waitcnt vmcnt(11)
	v_cndmask_b32_e64 v85, v59, 0, s[16:17]
	v_cndmask_b32_e64 v59, v54, 0, s[16:17]
	v_lshlrev_b32_e32 v50, 16, v51
	v_and_b32_e32 v51, 0xffff0000, v51
	v_cndmask_b32_e64 v89, v61, 0, s[16:17]
	v_cndmask_b32_e64 v83, v58, 0, s[16:17]
	v_cndmask_b32_e64 v61, v55, 0, s[16:17]
	v_cndmask_b32_e64 v55, v52, 0, s[16:17]
	s_waitcnt lgkmcnt(13)
	v_pk_fma_f32 v[50:51], v[10:11], v[50:51], v[42:43]
	v_lshlrev_b32_e32 v52, 16, v53
	v_and_b32_e32 v53, 0xffff0000, v53
	v_lshlrev_b32_e32 v58, 16, v59
	v_and_b32_e32 v59, 0xffff0000, v59
	v_cndmask_b32_e64 v87, v60, 0, s[16:17]
	v_cndmask_b32_e64 v79, v56, 0, s[16:17]
	v_pk_fma_f32 v[52:53], v[12:13], v[52:53], v[44:45]
	v_lshlrev_b32_e32 v54, 16, v55
	v_and_b32_e32 v55, 0xffff0000, v55
	v_lshlrev_b32_e32 v56, 16, v57
	v_and_b32_e32 v57, 0xffff0000, v57
	v_pk_fma_f32 v[50:51], v[18:19], v[58:59], v[50:51]
	v_lshlrev_b32_e32 v60, 16, v61
	v_and_b32_e32 v61, 0xffff0000, v61
	v_lshlrev_b32_e32 v82, 16, v83
	v_and_b32_e32 v83, 0xffff0000, v83
	s_waitcnt lgkmcnt(12)
	v_pk_fma_f32 v[54:55], v[14:15], v[54:55], v[46:47]
	v_pk_fma_f32 v[56:57], v[16:17], v[56:57], v[48:49]
	v_pk_fma_f32 v[52:53], v[20:21], v[60:61], v[52:53]
	v_lshlrev_b32_e32 v78, 16, v79
	v_and_b32_e32 v79, 0xffff0000, v79
	v_lshlrev_b32_e32 v80, 16, v81
	v_and_b32_e32 v81, 0xffff0000, v81
	v_pk_fma_f32 v[50:51], v[26:27], v[82:83], v[50:51]
	v_lshlrev_b32_e32 v84, 16, v85
	v_and_b32_e32 v85, 0xffff0000, v85
	s_waitcnt vmcnt(10)
	v_lshlrev_b32_e32 v90, 16, v62
	v_and_b32_e32 v91, 0xffff0000, v62
	v_pk_fma_f32 v[54:55], v[22:23], v[78:79], v[54:55]
	v_pk_fma_f32 v[56:57], v[24:25], v[80:81], v[56:57]
	v_pk_fma_f32 v[52:53], v[28:29], v[84:85], v[52:53]
	v_lshlrev_b32_e32 v86, 16, v87
	v_and_b32_e32 v87, 0xffff0000, v87
	v_lshlrev_b32_e32 v88, 16, v89
	v_and_b32_e32 v89, 0xffff0000, v89
	v_pk_fma_f32 v[50:51], v[34:35], v[90:91], v[50:51]
	v_lshlrev_b32_e32 v62, 16, v63
	v_and_b32_e32 v63, 0xffff0000, v63
	v_pk_fma_f32 v[54:55], v[30:31], v[86:87], v[54:55]
	v_pk_fma_f32 v[56:57], v[32:33], v[88:89], v[56:57]
	v_pk_fma_f32 v[52:53], v[36:37], v[62:63], v[52:53]
	v_lshlrev_b32_e32 v92, 16, v64
	v_and_b32_e32 v93, 0xffff0000, v64
	v_lshlrev_b32_e32 v64, 16, v65
	v_and_b32_e32 v65, 0xffff0000, v65
	v_cvt_pk_bf16_f32 v50, v50, v51
	v_cvt_pk_bf16_f32 v51, v52, v53
	v_pk_fma_f32 v[54:55], v[38:39], v[92:93], v[54:55]
	v_pk_fma_f32 v[56:57], v[40:41], v[64:65], v[56:57]
	v_cvt_pk_bf16_f32 v52, v54, v55
	v_pk_fma_f32 v[54:55], v[14:15], v[78:79], v[46:47]
	v_cvt_pk_bf16_f32 v53, v56, v57
	ds_write_b128 v247, v[50:53]
	v_pk_fma_f32 v[50:51], v[10:11], v[58:59], v[42:43]
	v_pk_fma_f32 v[52:53], v[12:13], v[60:61], v[44:45]
	v_pk_fma_f32 v[50:51], v[18:19], v[82:83], v[50:51]
	v_pk_fma_f32 v[56:57], v[16:17], v[80:81], v[48:49]
	v_pk_fma_f32 v[52:53], v[20:21], v[84:85], v[52:53]
	v_pk_fma_f32 v[50:51], v[26:27], v[90:91], v[50:51]
	s_waitcnt vmcnt(9)
; #define LAS __attribute__((address_space(3)))
; __device__ __forceinline__ unsigned cvt_pk_bf16(float lo, float hi) { unsigned r; asm volatile("v_cvt_pk_bf16_f32 %0, %1, %2" : "=v"(r) : "v"(lo), "v"(hi)); return r; }
; __device__ __forceinline__ float bflo(unsigned w) { return __uint_as_float(w << 16); }
; __device__ __forceinline__ float bfhi(unsigned w) { return __uint_as_float(w & 0xffff0000u); }
; template <int PASS> __device__ __forceinline__ void lru_wave_item(LAS unsigned char* lds, LAS unsigned char* vw, int b, int c, int h, const MixP& p, int lane, float (&Hrun)[8], bool cont) {
;     ...
; #pragma unroll
;         for (int jj = 0; jj < 4; ++jj) {
;             f32x2 o[4] = {bv[0], bv[1], bv[2], bv[3]};
; #pragma unroll
;             for (int k = 0; k < 4; ++k) { const u32x4 uk = ur[jj + k];
;                 o[0] = wv[k][0] * (f32x2){bflo(uk.x), bfhi(uk.x)} + o[0]; o[1] = wv[k][1] * (f32x2){bflo(uk.y), bfhi(uk.y)} + o[1];
;                 o[2] = wv[k][2] * (f32x2){bflo(uk.z), bfhi(uk.z)} + o[2]; o[3] = wv[k][3] * (f32x2){bflo(uk.w), bfhi(uk.w)} + o[3]; }
;             { u32x4 w; w.x = cvt_pk_bf16(o[0].x, o[0].y); w.y = cvt_pk_bf16(o[1].x, o[1].y); w.z = cvt_pk_bf16(o[2].x, o[2].y); w.w = cvt_pk_bf16(o[3].x, o[3].y);
;               *(LAS u32x4*)(vw + (4 * fq + jj) * WROW + cg * 16) = w; }
;         }
;         f32x4 aR[8], aI[8];
;         bf16x8 af[4];
;         {
; #pragma unroll
;             for (int kk = 0; kk < 4; ++kk) af[kk] = *(const LAS bf16x8*)(vw + fr * WROW + kk * 64 + fq * 16);
; #pragma unroll
;             for (int n = 0; n < 8; ++n) {
;                 aR[n] = (f32x4){0.f, 0.f, 0.f, 0.f}; aI[n] = (f32x4){0.f, 0.f, 0.f, 0.f};
; #pragma unroll
;                 for (int kk = 0; kk < 4; ++kk) {
;                     const bf16x8 ba = *(const LAS bf16x8*)(lds + WA_OFF + (16 * n + fr) * WROW + kk * 64 + fq * 16);
;                     const bf16x8 bx = *(const LAS bf16x8*)(lds + WX_OFF + (16 * n + fr) * WROW + kk * 64 + fq * 16);
;                     aR[n] = __builtin_amdgcn_mfma_f32_16x16x32_bf16(af[kk], ba, aR[n], 0, 0, 0);
;                     aI[n] = __builtin_amdgcn_mfma_f32_16x16x32_bf16(af[kk], bx, aI[n], 0, 0, 0);
;                 }
;             }
	v_lshlrev_b32_e32 v58, 16, v66
	v_and_b32_e32 v59, 0xffff0000, v66
	v_pk_fma_f32 v[54:55], v[22:23], v[86:87], v[54:55]
	v_pk_fma_f32 v[56:57], v[24:25], v[88:89], v[56:57]
	v_pk_fma_f32 v[52:53], v[28:29], v[62:63], v[52:53]
	v_pk_fma_f32 v[50:51], v[34:35], v[58:59], v[50:51]
	v_lshlrev_b32_e32 v60, 16, v67
	v_and_b32_e32 v61, 0xffff0000, v67
	v_pk_fma_f32 v[54:55], v[30:31], v[92:93], v[54:55]
	v_pk_fma_f32 v[56:57], v[32:33], v[64:65], v[56:57]
	v_pk_fma_f32 v[52:53], v[36:37], v[60:61], v[52:53]
	v_lshlrev_b32_e32 v66, 16, v68
	v_and_b32_e32 v67, 0xffff0000, v68
	v_lshlrev_b32_e32 v68, 16, v69
	v_and_b32_e32 v69, 0xffff0000, v69
	v_cvt_pk_bf16_f32 v50, v50, v51
	v_cvt_pk_bf16_f32 v51, v52, v53
	v_pk_fma_f32 v[54:55], v[38:39], v[66:67], v[54:55]
	v_pk_fma_f32 v[56:57], v[40:41], v[68:69], v[56:57]
	v_cvt_pk_bf16_f32 v52, v54, v55
	v_pk_fma_f32 v[54:55], v[14:15], v[86:87], v[46:47]
	v_cvt_pk_bf16_f32 v53, v56, v57
	ds_write_b128 v247, v[50:53] offset:272
	v_pk_fma_f32 v[50:51], v[10:11], v[82:83], v[42:43]
	v_pk_fma_f32 v[52:53], v[12:13], v[84:85], v[44:45]
	v_pk_fma_f32 v[50:51], v[18:19], v[90:91], v[50:51]
	v_pk_fma_f32 v[56:57], v[16:17], v[88:89], v[48:49]
	v_pk_fma_f32 v[52:53], v[20:21], v[62:63], v[52:53]
	v_pk_fma_f32 v[50:51], v[26:27], v[58:59], v[50:51]
	s_waitcnt vmcnt(8)
	v_lshlrev_b32_e32 v78, 16, v70
	v_and_b32_e32 v79, 0xffff0000, v70
	v_pk_fma_f32 v[54:55], v[22:23], v[92:93], v[54:55]
	v_pk_fma_f32 v[56:57], v[24:25], v[64:65], v[56:57]
	v_pk_fma_f32 v[52:53], v[28:29], v[60:61], v[52:53]
	v_pk_fma_f32 v[50:51], v[34:35], v[78:79], v[50:51]
	v_lshlrev_b32_e32 v70, 16, v71
	v_and_b32_e32 v71, 0xffff0000, v71
	v_pk_fma_f32 v[54:55], v[30:31], v[66:67], v[54:55]
	v_pk_fma_f32 v[56:57], v[32:33], v[68:69], v[56:57]
	v_pk_fma_f32 v[52:53], v[36:37], v[70:71], v[52:53]
	v_lshlrev_b32_e32 v80, 16, v72
	v_and_b32_e32 v81, 0xffff0000, v72
	v_lshlrev_b32_e32 v72, 16, v73
	v_and_b32_e32 v73, 0xffff0000, v73
	v_cvt_pk_bf16_f32 v50, v50, v51
	v_cvt_pk_bf16_f32 v51, v52, v53
	v_pk_fma_f32 v[54:55], v[38:39], v[80:81], v[54:55]
	v_pk_fma_f32 v[56:57], v[40:41], v[72:73], v[56:57]
	v_cvt_pk_bf16_f32 v52, v54, v55
	v_pk_fma_f32 v[54:55], v[14:15], v[92:93], v[46:47]
	v_cvt_pk_bf16_f32 v53, v56, v57
	ds_write_b128 v247, v[50:53] offset:544
	v_pk_fma_f32 v[50:51], v[10:11], v[90:91], v[42:43]
	v_pk_fma_f32 v[52:53], v[12:13], v[62:63], v[44:45]
	v_pk_fma_f32 v[50:51], v[18:19], v[58:59], v[50:51]
	v_pk_fma_f32 v[52:53], v[20:21], v[60:61], v[52:53]
	v_pk_fma_f32 v[50:51], v[26:27], v[78:79], v[50:51]
	s_waitcnt vmcnt(7)
	v_lshlrev_b32_e32 v58, 16, v74
	v_and_b32_e32 v59, 0xffff0000, v74
	v_pk_fma_f32 v[56:57], v[16:17], v[64:65], v[48:49]
	v_pk_fma_f32 v[54:55], v[22:23], v[66:67], v[54:55]
	v_pk_fma_f32 v[52:53], v[28:29], v[70:71], v[52:53]
	v_pk_fma_f32 v[50:51], v[34:35], v[58:59], v[50:51]
	v_lshlrev_b32_e32 v58, 16, v75
	v_and_b32_e32 v59, 0xffff0000, v75
	v_pk_fma_f32 v[56:57], v[24:25], v[68:69], v[56:57]
	v_pk_fma_f32 v[54:55], v[30:31], v[80:81], v[54:55]
	v_pk_fma_f32 v[52:53], v[36:37], v[58:59], v[52:53]
	v_lshlrev_b32_e32 v58, 16, v76
	v_and_b32_e32 v59, 0xffff0000, v76
	v_pk_fma_f32 v[56:57], v[32:33], v[72:73], v[56:57]
	v_pk_fma_f32 v[54:55], v[38:39], v[58:59], v[54:55]
	v_lshlrev_b32_e32 v58, 16, v77
	v_and_b32_e32 v59, 0xffff0000, v77
	v_cvt_pk_bf16_f32 v50, v50, v51
	v_pk_fma_f32 v[56:57], v[40:41], v[58:59], v[56:57]
	v_cvt_pk_bf16_f32 v51, v52, v53
	v_cvt_pk_bf16_f32 v52, v54, v55
	v_add_u32_e32 v74, v234, v235
	v_cvt_pk_bf16_f32 v53, v56, v57
	ds_write_b128 v247, v[50:53] offset:816
	v_add_u32_e32 v50, v232, v233
	ds_read_b128 v[110:113], v50
	ds_read_b128 v[82:85], v50 offset:64
	ds_read_b128 v[54:57], v50 offset:128
	ds_read_b128 v[50:53], v50 offset:192
	ds_read_b128 v[58:61], v138
	ds_read_b128 v[62:65], v138 offset:34816
	ds_read_b128 v[66:69], v138 offset:64
	ds_read_b128 v[70:73], v138 offset:34880
	s_waitcnt lgkmcnt(3)
	v_mfma_f32_16x16x32_bf16 v[58:61], v[110:113], v[58:61], 0
	s_waitcnt lgkmcnt(2)
	v_mfma_f32_16x16x32_bf16 v[62:65], v[110:113], v[62:65], 0
	s_waitcnt lgkmcnt(1)
	v_mfma_f32_16x16x32_bf16 v[58:61], v[82:85], v[66:69], v[58:61]
	s_waitcnt lgkmcnt(0)
	v_mfma_f32_16x16x32_bf16 v[62:65], v[82:85], v[70:73], v[62:65]
	ds_read_b128 v[66:69], v138 offset:128
	ds_read_b128 v[70:73], v138 offset:34944
	s_waitcnt lgkmcnt(1)
	v_mfma_f32_16x16x32_bf16 v[58:61], v[54:57], v[66:69], v[58:61]
	s_waitcnt lgkmcnt(0)
	v_mfma_f32_16x16x32_bf16 v[62:65], v[54:57], v[70:73], v[62:65]
	ds_read_b128 v[66:69], v138 offset:192
	ds_read_b128 v[70:73], v138 offset:35008
	s_waitcnt lgkmcnt(1)
	v_mfma_f32_16x16x32_bf16 v[126:129], v[50:53], v[66:69], v[58:61]
	s_waitcnt lgkmcnt(0)
	v_mfma_f32_16x16x32_bf16 v[122:125], v[50:53], v[70:73], v[62:65]
	s_nop 0
	ds_read_b128 v[58:61], v138 offset:4352
	s_nop 0
	ds_read_b128 v[62:65], v138 offset:39168
	ds_read_b128 v[66:69], v138 offset:4416
	ds_read_b128 v[70:73], v138 offset:39232
	v_add_f32_e32 v126, v170, v126
	s_waitcnt lgkmcnt(3)
	v_mfma_f32_16x16x32_bf16 v[58:61], v[110:113], v[58:61], 0
	v_add_f32_e32 v127, v170, v127
	v_mul_f32_e32 v126, 0xbfb8aa3b, v126
	v_mul_f32_e32 v127, 0xbfb8aa3b, v127
	s_waitcnt lgkmcnt(2)
	v_mfma_f32_16x16x32_bf16 v[62:65], v[110:113], v[62:65], 0
	v_exp_f32_e32 v126, v126
	v_exp_f32_e32 v127, v127
	v_add_f32_e32 v122, v174, v122
	s_waitcnt lgkmcnt(1)
	v_mfma_f32_16x16x32_bf16 v[58:61], v[82:85], v[66:69], v[58:61]
	v_add_f32_e32 v126, 1.0, v126
	v_add_f32_e32 v127, 1.0, v127
	v_rcp_f32_e32 v126, v126
	s_waitcnt lgkmcnt(0)
; #define LAS __attribute__((address_space(3)))
; __device__ __forceinline__ float fsig2(float x) { return __builtin_amdgcn_rcpf(1.0f + __builtin_amdgcn_exp2f(-LOG2E * x)); }
; template <int PASS> __device__ __forceinline__ void lru_wave_item(LAS unsigned char* lds, LAS unsigned char* vw, int b, int c, int h, const MixP& p, int lane, float (&Hrun)[8], bool cont) {
;     ...
;             for (int kk = 0; kk < 4; ++kk) af[kk] = *(const LAS bf16x8*)(vw + fr * WROW + kk * 64 + fq * 16);
; #pragma unroll
;             for (int n = 0; n < 8; ++n) {
;                 aR[n] = (f32x4){0.f, 0.f, 0.f, 0.f}; aI[n] = (f32x4){0.f, 0.f, 0.f, 0.f};
; #pragma unroll
;                 for (int kk = 0; kk < 4; ++kk) {
;                     const bf16x8 ba = *(const LAS bf16x8*)(lds + WA_OFF + (16 * n + fr) * WROW + kk * 64 + fq * 16);
;                     const bf16x8 bx = *(const LAS bf16x8*)(lds + WX_OFF + (16 * n + fr) * WROW + kk * 64 + fq * 16);
;                     aR[n] = __builtin_amdgcn_mfma_f32_16x16x32_bf16(af[kk], ba, aR[n], 0, 0, 0);
;                     aI[n] = __builtin_amdgcn_mfma_f32_16x16x32_bf16(af[kk], bx, aI[n], 0, 0, 0);
;                 }
;             }
;         }
; #pragma unroll
;         for (int n = 0; n < 8; ++n) {
;             const f32x4 aVn = __builtin_amdgcn_mfma_f32_16x16x32_bf16(af[n >> 1], idf[n & 1], (f32x4){0.f, 0.f, 0.f, 0.f}, 0, 0, 0);
;             float av[4], bxv[4];
; #pragma unroll
;             for (int j = 0; j < 4; ++j) {
;                 const float r = fsig2(aR[n][j] + pba[n]), ig = fsig2(aI[n][j] + pbx[n]);
;                 const float a = __builtin_amdgcn_exp2f(r * pk8[n]), mult = __builtin_amdgcn_sqrtf(fmaxf(1.0f - a * a, 0.f));
	v_mfma_f32_16x16x32_bf16 v[62:65], v[82:85], v[70:73], v[62:65]
	ds_read_b128 v[66:69], v138 offset:4480
	ds_read_b128 v[70:73], v138 offset:39296
	v_rcp_f32_e32 v127, v127
	v_mul_f32_e32 v126, v176, v126
	s_waitcnt lgkmcnt(1)
	v_mfma_f32_16x16x32_bf16 v[58:61], v[54:57], v[66:69], v[58:61]
	v_add_f32_e32 v123, v174, v123
	v_mul_f32_e32 v127, v176, v127
	v_mul_f32_e32 v122, 0xbfb8aa3b, v122
	s_waitcnt lgkmcnt(0)
	v_mfma_f32_16x16x32_bf16 v[62:65], v[54:57], v[70:73], v[62:65]
	ds_read_b128 v[66:69], v138 offset:4544
	ds_read_b128 v[70:73], v138 offset:39360
	v_mul_f32_e32 v123, 0xbfb8aa3b, v123
	v_exp_f32_e32 v122, v122
	s_waitcnt lgkmcnt(1)
	v_mfma_f32_16x16x32_bf16 v[118:121], v[50:53], v[66:69], v[58:61]
	v_exp_f32_e32 v123, v123
	v_add_f32_e32 v122, 1.0, v122
	v_rcp_f32_e32 v122, v122
	s_waitcnt lgkmcnt(0)
	v_mfma_f32_16x16x32_bf16 v[114:117], v[50:53], v[70:73], v[62:65]
	ds_read_b128 v[58:61], v138 offset:8704
	s_nop 1
	ds_read_b128 v[62:65], v138 offset:43520
	ds_read_b128 v[66:69], v138 offset:8768
	ds_read_b128 v[70:73], v138 offset:43584
	v_add_f32_e32 v123, 1.0, v123
	s_waitcnt lgkmcnt(3)
	v_mfma_f32_16x16x32_bf16 v[58:61], v[110:113], v[58:61], 0
	v_rcp_f32_e32 v123, v123
	v_add_f32_e32 v124, v174, v124
	v_add_f32_e32 v125, v174, v125
	s_waitcnt lgkmcnt(2)
	v_mfma_f32_16x16x32_bf16 v[62:65], v[110:113], v[62:65], 0
	v_mul_f32_e32 v124, 0xbfb8aa3b, v124
	v_mul_f32_e32 v125, 0xbfb8aa3b, v125
	v_exp_f32_e32 v124, v124
	s_waitcnt lgkmcnt(1)
	v_mfma_f32_16x16x32_bf16 v[58:61], v[82:85], v[66:69], v[58:61]
	v_exp_f32_e32 v125, v125
	v_add_f32_e32 v118, v171, v118
	v_add_f32_e32 v119, v171, v119
	s_waitcnt lgkmcnt(0)
	v_mfma_f32_16x16x32_bf16 v[62:65], v[82:85], v[70:73], v[62:65]
	ds_read_b128 v[66:69], v138 offset:8832
	ds_read_b128 v[70:73], v138 offset:43648
	v_add_f32_e32 v124, 1.0, v124
	v_add_f32_e32 v125, 1.0, v125
	s_waitcnt lgkmcnt(1)
	v_mfma_f32_16x16x32_bf16 v[58:61], v[54:57], v[66:69], v[58:61]
	v_mul_f32_e32 v118, 0xbfb8aa3b, v118
	v_mul_f32_e32 v119, 0xbfb8aa3b, v119
	v_rcp_f32_e32 v124, v124
	s_waitcnt lgkmcnt(0)
	v_mfma_f32_16x16x32_bf16 v[62:65], v[54:57], v[70:73], v[62:65]
	ds_read_b128 v[66:69], v138 offset:8896
	ds_read_b128 v[70:73], v138 offset:43712
	v_exp_f32_e32 v118, v118
	v_exp_f32_e32 v119, v119
	s_waitcnt lgkmcnt(1)
	v_mfma_f32_16x16x32_bf16 v[106:109], v[50:53], v[66:69], v[58:61]
	v_add_f32_e32 v118, 1.0, v118
	v_add_f32_e32 v119, 1.0, v119
	v_rcp_f32_e32 v118, v118
	s_waitcnt lgkmcnt(0)
	v_mfma_f32_16x16x32_bf16 v[102:105], v[50:53], v[70:73], v[62:65]
	ds_read_b128 v[58:61], v74
	s_nop 1
	ds_read_b128 v[62:65], v74 offset:34816
	ds_read_b128 v[66:69], v74 offset:64
	ds_read_b128 v[70:73], v74 offset:34880
	v_rcp_f32_e32 v119, v119
	s_waitcnt lgkmcnt(3)
	v_mfma_f32_16x16x32_bf16 v[58:61], v[110:113], v[58:61], 0
	v_add_f32_e32 v114, v175, v114
	v_mul_f32_e32 v118, v177, v118
	v_add_f32_e32 v115, v175, v115
	s_waitcnt lgkmcnt(2)
	v_mfma_f32_16x16x32_bf16 v[62:65], v[110:113], v[62:65], 0
	v_mul_f32_e32 v119, v177, v119
	v_mul_f32_e32 v114, 0xbfb8aa3b, v114
	v_mul_f32_e32 v115, 0xbfb8aa3b, v115
	s_waitcnt lgkmcnt(1)
	v_mfma_f32_16x16x32_bf16 v[58:61], v[82:85], v[66:69], v[58:61]
	v_exp_f32_e32 v114, v114
	v_exp_f32_e32 v115, v115
	v_add_f32_e32 v106, v178, v106
	s_waitcnt lgkmcnt(0)
	v_mfma_f32_16x16x32_bf16 v[62:65], v[82:85], v[70:73], v[62:65]
	ds_read_b128 v[66:69], v74 offset:128
	ds_read_b128 v[70:73], v74 offset:34944
	v_add_f32_e32 v114, 1.0, v114
	v_add_f32_e32 v115, 1.0, v115
	s_waitcnt lgkmcnt(1)
	v_mfma_f32_16x16x32_bf16 v[58:61], v[54:57], v[66:69], v[58:61]
	v_rcp_f32_e32 v114, v114
	v_rcp_f32_e32 v115, v115
	v_add_f32_e32 v107, v178, v107
	s_waitcnt lgkmcnt(0)
	v_mfma_f32_16x16x32_bf16 v[62:65], v[54:57], v[70:73], v[62:65]
	ds_read_b128 v[66:69], v74 offset:192
	ds_read_b128 v[70:73], v74 offset:35008
	v_mul_f32_e32 v106, 0xbfb8aa3b, v106
	v_mul_f32_e32 v107, 0xbfb8aa3b, v107
	s_waitcnt lgkmcnt(1)
	v_mfma_f32_16x16x32_bf16 v[90:93], v[50:53], v[66:69], v[58:61]
	v_exp_f32_e32 v106, v106
	v_exp_f32_e32 v107, v107
	v_add_f32_e32 v102, v180, v102
	s_waitcnt lgkmcnt(0)
	v_mfma_f32_16x16x32_bf16 v[86:89], v[50:53], v[70:73], v[62:65]
	ds_read_b128 v[58:61], v138 offset:17408
	s_nop 1
	ds_read_b128 v[62:65], v138 offset:52224
	ds_read_b128 v[66:69], v138 offset:17472
	ds_read_b128 v[70:73], v138 offset:52288
	v_add_f32_e32 v106, 1.0, v106
	s_waitcnt lgkmcnt(3)
	v_mfma_f32_16x16x32_bf16 v[58:61], v[110:113], v[58:61], 0
	v_add_f32_e32 v107, 1.0, v107
	v_rcp_f32_e32 v106, v106
	v_rcp_f32_e32 v107, v107
	s_waitcnt lgkmcnt(2)
	v_mfma_f32_16x16x32_bf16 v[62:65], v[110:113], v[62:65], 0
	v_add_f32_e32 v103, v180, v103
	v_mul_f32_e32 v106, v182, v106
	v_mul_f32_e32 v107, v182, v107
	s_waitcnt lgkmcnt(1)
	v_mfma_f32_16x16x32_bf16 v[58:61], v[82:85], v[66:69], v[58:61]
	v_mul_f32_e32 v102, 0xbfb8aa3b, v102
	v_mul_f32_e32 v103, 0xbfb8aa3b, v103
	v_exp_f32_e32 v102, v102
	s_waitcnt lgkmcnt(0)
	v_mfma_f32_16x16x32_bf16 v[62:65], v[82:85], v[70:73], v[62:65]
	ds_read_b128 v[66:69], v138 offset:17536
	ds_read_b128 v[70:73], v138 offset:52352
	v_exp_f32_e32 v103, v103
	v_add_f32_e32 v102, 1.0, v102
	s_waitcnt lgkmcnt(1)
	v_mfma_f32_16x16x32_bf16 v[58:61], v[54:57], v[66:69], v[58:61]
	v_add_f32_e32 v103, 1.0, v103
	v_rcp_f32_e32 v102, v102
	v_rcp_f32_e32 v103, v103
	s_waitcnt lgkmcnt(0)
	v_mfma_f32_16x16x32_bf16 v[62:65], v[54:57], v[70:73], v[62:65]
	ds_read_b128 v[66:69], v138 offset:17600
	ds_read_b128 v[70:73], v138 offset:52416
	v_add_f32_e32 v104, v180, v104
	v_add_f32_e32 v105, v180, v105
	s_waitcnt lgkmcnt(1)
; #define LAS __attribute__((address_space(3)))
; __device__ __forceinline__ float fsig2(float x) { return __builtin_amdgcn_rcpf(1.0f + __builtin_amdgcn_exp2f(-LOG2E * x)); }
; template <int PASS> __device__ __forceinline__ void lru_wave_item(LAS unsigned char* lds, LAS unsigned char* vw, int b, int c, int h, const MixP& p, int lane, float (&Hrun)[8], bool cont) {
;     ...
;             for (int kk = 0; kk < 4; ++kk) af[kk] = *(const LAS bf16x8*)(vw + fr * WROW + kk * 64 + fq * 16);
; #pragma unroll
;             for (int n = 0; n < 8; ++n) {
;                 aR[n] = (f32x4){0.f, 0.f, 0.f, 0.f}; aI[n] = (f32x4){0.f, 0.f, 0.f, 0.f};
; #pragma unroll
;                 for (int kk = 0; kk < 4; ++kk) {
;                     const bf16x8 ba = *(const LAS bf16x8*)(lds + WA_OFF + (16 * n + fr) * WROW + kk * 64 + fq * 16);
;                     const bf16x8 bx = *(const LAS bf16x8*)(lds + WX_OFF + (16 * n + fr) * WROW + kk * 64 + fq * 16);
;                     aR[n] = __builtin_amdgcn_mfma_f32_16x16x32_bf16(af[kk], ba, aR[n], 0, 0, 0);
;                     aI[n] = __builtin_amdgcn_mfma_f32_16x16x32_bf16(af[kk], bx, aI[n], 0, 0, 0);
;                 }
;             }
;         }
; #pragma unroll
;         for (int n = 0; n < 8; ++n) {
;             const f32x4 aVn = __builtin_amdgcn_mfma_f32_16x16x32_bf16(af[n >> 1], idf[n & 1], (f32x4){0.f, 0.f, 0.f, 0.f}, 0, 0, 0);
;             float av[4], bxv[4];
; #pragma unroll
;             for (int j = 0; j < 4; ++j) {
;                 const float r = fsig2(aR[n][j] + pba[n]), ig = fsig2(aI[n][j] + pbx[n]);
;                 const float a = __builtin_amdgcn_exp2f(r * pk8[n]), mult = __builtin_amdgcn_sqrtf(fmaxf(1.0f - a * a, 0.f));
;                 av[j] = a; bxv[j] = mult * ig * aVn[j];
;             }
	v_mfma_f32_16x16x32_bf16 v[78:81], v[50:53], v[66:69], v[58:61]
	v_mul_f32_e32 v104, 0xbfb8aa3b, v104
	v_mul_f32_e32 v105, 0xbfb8aa3b, v105
	v_exp_f32_e32 v104, v104
	s_waitcnt lgkmcnt(0)
	v_mfma_f32_16x16x32_bf16 v[74:77], v[50:53], v[70:73], v[62:65]
	ds_read_b128 v[58:61], v138 offset:21760
	s_nop 1
	ds_read_b128 v[62:65], v138 offset:56576
	ds_read_b128 v[66:69], v138 offset:21824
	ds_read_b128 v[70:73], v138 offset:56640
	v_exp_f32_e32 v105, v105
	s_waitcnt lgkmcnt(3)
	v_mfma_f32_16x16x32_bf16 v[58:61], v[110:113], v[58:61], 0
	v_add_f32_e32 v104, 1.0, v104
	v_add_f32_e32 v105, 1.0, v105
	v_rcp_f32_e32 v104, v104
	s_waitcnt lgkmcnt(2)
	v_mfma_f32_16x16x32_bf16 v[62:65], v[110:113], v[62:65], 0
	v_add_f32_e32 v90, v179, v90
	v_add_f32_e32 v91, v179, v91
	v_mul_f32_e32 v90, 0xbfb8aa3b, v90
	s_waitcnt lgkmcnt(1)
	v_mfma_f32_16x16x32_bf16 v[58:61], v[82:85], v[66:69], v[58:61]
	v_mul_f32_e32 v91, 0xbfb8aa3b, v91
	v_exp_f32_e32 v90, v90
	v_exp_f32_e32 v91, v91
	s_waitcnt lgkmcnt(0)
	v_mfma_f32_16x16x32_bf16 v[62:65], v[82:85], v[70:73], v[62:65]
	ds_read_b128 v[66:69], v138 offset:21888
	ds_read_b128 v[70:73], v138 offset:56704
	v_add_f32_e32 v90, 1.0, v90
	v_add_f32_e32 v91, 1.0, v91
	s_waitcnt lgkmcnt(1)
	v_mfma_f32_16x16x32_bf16 v[58:61], v[54:57], v[66:69], v[58:61]
	ds_read_b128 v[66:69], v138 offset:21952
	ds_read_b128 v[94:97], v138 offset:56768
	v_rcp_f32_e32 v90, v90
	v_rcp_f32_e32 v91, v91
	s_waitcnt lgkmcnt(2)
	v_mfma_f32_16x16x32_bf16 v[62:65], v[54:57], v[70:73], v[62:65]
	v_add_f32_e32 v86, v181, v86
	v_mul_f32_e32 v90, v183, v90
	v_add_f32_e32 v87, v181, v87
	s_waitcnt lgkmcnt(1)
	v_mfma_f32_16x16x32_bf16 v[70:73], v[50:53], v[66:69], v[58:61]
	v_mul_f32_e32 v91, v183, v91
	v_mul_f32_e32 v86, 0xbfb8aa3b, v86
	v_mul_f32_e32 v87, 0xbfb8aa3b, v87
	s_waitcnt lgkmcnt(0)
	v_mfma_f32_16x16x32_bf16 v[66:69], v[50:53], v[94:97], v[62:65]
	ds_read_b128 v[58:61], v138 offset:26112
	s_nop 1
	ds_read_b128 v[62:65], v138 offset:60928
	ds_read_b128 v[94:97], v138 offset:26176
	ds_read_b128 v[98:101], v138 offset:60992
	v_exp_f32_e32 v86, v86
	s_waitcnt lgkmcnt(3)
	v_mfma_f32_16x16x32_bf16 v[58:61], v[110:113], v[58:61], 0
	v_exp_f32_e32 v87, v87
	v_add_f32_e32 v86, 1.0, v86
	v_rcp_f32_e32 v86, v86
	s_waitcnt lgkmcnt(2)
	v_mfma_f32_16x16x32_bf16 v[62:65], v[110:113], v[62:65], 0
	v_add_f32_e32 v87, 1.0, v87
	v_rcp_f32_e32 v87, v87
	v_add_f32_e32 v78, v184, v78
	s_waitcnt lgkmcnt(1)
	v_mfma_f32_16x16x32_bf16 v[58:61], v[82:85], v[94:97], v[58:61]
	v_add_f32_e32 v79, v184, v79
	v_mul_f32_e32 v78, 0xbfb8aa3b, v78
	v_mul_f32_e32 v79, 0xbfb8aa3b, v79
	s_waitcnt lgkmcnt(0)
	v_mfma_f32_16x16x32_bf16 v[62:65], v[82:85], v[98:101], v[62:65]
	ds_read_b128 v[94:97], v138 offset:26240
	ds_read_b128 v[98:101], v138 offset:61056
	v_exp_f32_e32 v78, v78
	v_exp_f32_e32 v79, v79
	s_waitcnt lgkmcnt(1)
	v_mfma_f32_16x16x32_bf16 v[58:61], v[54:57], v[94:97], v[58:61]
	v_add_f32_e32 v78, 1.0, v78
	v_add_f32_e32 v79, 1.0, v79
	v_rcp_f32_e32 v78, v78
	s_waitcnt lgkmcnt(0)
	v_mfma_f32_16x16x32_bf16 v[94:97], v[54:57], v[98:101], v[62:65]
	s_nop 2
	ds_read_b128 v[62:65], v138 offset:26304
	ds_read_b128 v[98:101], v138 offset:61120
	v_rcp_f32_e32 v79, v79
	v_add_f32_e32 v74, v186, v74
	s_waitcnt lgkmcnt(1)
	v_mfma_f32_16x16x32_bf16 v[62:65], v[50:53], v[62:65], v[58:61]
	v_mul_f32_e32 v78, v188, v78
	v_add_f32_e32 v75, v186, v75
	v_mul_f32_e32 v79, v188, v79
	s_waitcnt lgkmcnt(0)
	v_mfma_f32_16x16x32_bf16 v[58:61], v[50:53], v[98:101], v[94:97]
	v_mul_f32_e32 v74, 0xbfb8aa3b, v74
	v_mul_f32_e32 v75, 0xbfb8aa3b, v75
	v_exp_f32_e32 v74, v74
	v_add_u32_e32 v94, v234, v236
	ds_read_b128 v[96:99], v94
	ds_read_b128 v[198:201], v94 offset:34816
	ds_read_b128 v[202:205], v94 offset:64
	ds_read_b128 v[138:141], v94 offset:34880
	s_waitcnt lgkmcnt(3)
	v_mfma_f32_16x16x32_bf16 v[96:99], v[110:113], v[96:99], 0
	v_exp_f32_e32 v75, v75
	v_add_f32_e32 v74, 1.0, v74
	v_rcp_f32_e32 v74, v74
	s_waitcnt lgkmcnt(2)
	v_mfma_f32_16x16x32_bf16 v[198:201], v[110:113], v[198:201], 0
	v_add_f32_e32 v75, 1.0, v75
	v_rcp_f32_e32 v75, v75
	v_add_f32_e32 v76, v186, v76
	s_waitcnt lgkmcnt(1)
	v_mfma_f32_16x16x32_bf16 v[96:99], v[82:85], v[202:205], v[96:99]
	v_add_f32_e32 v77, v186, v77
	v_mul_f32_e32 v76, 0xbfb8aa3b, v76
	v_mul_f32_e32 v77, 0xbfb8aa3b, v77
	s_waitcnt lgkmcnt(0)
	v_mfma_f32_16x16x32_bf16 v[138:141], v[82:85], v[138:141], v[198:201]
	s_nop 2
	ds_read_b128 v[198:201], v94 offset:128
	ds_read_b128 v[202:205], v94 offset:34944
	v_exp_f32_e32 v76, v76
	v_exp_f32_e32 v77, v77
	s_waitcnt lgkmcnt(1)
	v_mfma_f32_16x16x32_bf16 v[96:99], v[54:57], v[198:201], v[96:99]
	v_add_f32_e32 v76, 1.0, v76
	v_add_f32_e32 v77, 1.0, v77
	v_rcp_f32_e32 v76, v76
	s_waitcnt lgkmcnt(0)
	v_mfma_f32_16x16x32_bf16 v[138:141], v[54:57], v[202:205], v[138:141]
	ds_read_b128 v[198:201], v94 offset:192
	ds_read_b128 v[202:205], v94 offset:35008
	v_add_f32_e32 v70, v185, v70
	v_add_f32_e32 v71, v185, v71
	s_waitcnt lgkmcnt(1)
	v_mfma_f32_16x16x32_bf16 v[98:101], v[50:53], v[198:201], v[96:99]
	v_exp_f32_e32 v198, v126
	v_exp_f32_e32 v199, v127
	v_mul_f32_e32 v70, 0xbfb8aa3b, v70
	s_waitcnt lgkmcnt(0)
; __device__ __forceinline__ float fsig2(float x) { return __builtin_amdgcn_rcpf(1.0f + __builtin_amdgcn_exp2f(-LOG2E * x)); }
; template <int PASS> __device__ __forceinline__ void lru_wave_item(LAS unsigned char* lds, LAS unsigned char* vw, int b, int c, int h, const MixP& p, int lane, float (&Hrun)[8], bool cont) {
;     ...
;         for (int n = 0; n < 8; ++n) {
;             const f32x4 aVn = __builtin_amdgcn_mfma_f32_16x16x32_bf16(af[n >> 1], idf[n & 1], (f32x4){0.f, 0.f, 0.f, 0.f}, 0, 0, 0);
;             float av[4], bxv[4];
; #pragma unroll
;             for (int j = 0; j < 4; ++j) {
;                 const float r = fsig2(aR[n][j] + pba[n]), ig = fsig2(aI[n][j] + pbx[n]);
;                 const float a = __builtin_amdgcn_exp2f(r * pk8[n]), mult = __builtin_amdgcn_sqrtf(fmaxf(1.0f - a * a, 0.f));
;                 av[j] = a; bxv[j] = mult * ig * aVn[j];
;             }
;             const float H0 = bxv[0], H1 = av[1] * H0 + bxv[1], H2 = av[2] * H1 + bxv[2], H3 = av[3] * H2 + bxv[3];
;             const float A0 = av[0], A1 = av[1] * A0, A2 = av[2] * A1, A3 = av[3] * A2;
;             float At[4], Ht[4];
; #pragma unroll
;             for (int q = 0; q < 4; ++q) { At[q] = __shfl(A3, fr + 16 * q); Ht[q] = __shfl(H3, fr + 16 * q); }
;             const float c0 = Hrun[n], c1 = At[0] * c0 + Ht[0], c2 = At[1] * c1 + Ht[1], c3 = At[2] * c2 + Ht[2], c4 = At[3] * c3 + Ht[3];
;             Hrun[n] = c4;
;             if (PASS == 1) Arun[n] *= (At[0] * At[1]) * (At[2] * At[3]);
	v_mfma_f32_16x16x32_bf16 v[94:97], v[50:53], v[202:205], v[138:141]
	v_fma_f32 v126, -v198, v198, 1.0
	v_fma_f32 v127, -v199, v199, 1.0
	v_max_f32_e32 v126, 0, v126
	v_max_f32_e32 v127, 0, v127
	v_sqrt_f32_e32 v126, v126
	v_sqrt_f32_e32 v127, v127
	v_and_or_b32 v138, v213, 64, v137
	v_lshlrev_b32_e32 v151, 2, v138
	v_mfma_f32_16x16x32_bf16 v[138:141], v[110:113], v[2:5], 0
	v_mul_f32_e64 v122, v122, v126
	v_mul_f32_e64 v123, v123, v127
	v_add_f32_e32 v126, v170, v128
	v_mul_f32_e32 v126, 0xbfb8aa3b, v126
	v_exp_f32_e32 v126, v126
	v_rcp_f32_e32 v128, v125
	s_nop 1
	v_pk_mul_f32 v[122:123], v[122:123], v[138:139]
	v_mfma_f32_16x16x32_bf16 v[110:113], v[110:113], v[6:9], 0
	v_add_f32_e32 v126, 1.0, v126
	v_rcp_f32_e32 v126, v126
	v_fmac_f32_e32 v123, v199, v122
	v_mul_f32_e32 v71, 0xbfb8aa3b, v71
	v_exp_f32_e32 v70, v70
	v_mul_f32_e32 v126, v176, v126
	v_exp_f32_e32 v127, v126
	v_add_f32_e32 v126, v170, v129
	v_mul_f32_e32 v126, 0xbfb8aa3b, v126
	v_exp_f32_e32 v126, v126
	v_fma_f32 v122, -v127, v127, 1.0
	v_max_f32_e32 v122, 0, v122
	v_exp_f32_e32 v71, v71
	v_add_f32_e32 v126, 1.0, v126
	v_rcp_f32_e32 v126, v126
	v_add_f32_e32 v70, 1.0, v70
	v_add_f32_e32 v71, 1.0, v71
	v_rcp_f32_e32 v70, v70
	v_mul_f32_e32 v125, v176, v126
	v_sqrt_f32_e32 v126, v122
	v_exp_f32_e32 v139, v125
	v_mov_b32_e32 v125, v123
	v_rcp_f32_e32 v71, v71
	v_pk_mul_f32 v[122:123], v[124:125], v[126:127]
	v_exp_f32_e32 v124, v119
	v_fmac_f32_e32 v123, v122, v140
	v_fma_f32 v122, -v139, v139, 1.0
	v_max_f32_e32 v122, 0, v122
	v_sqrt_f32_e32 v138, v122
	v_mul_f32_e32 v122, v199, v198
	v_mul_f32_e32 v122, v127, v122
	v_mul_f32_e32 v122, v139, v122
	v_mov_b32_e32 v129, v123
	ds_bpermute_b32 v123, v151, v122
	ds_bpermute_b32 v127, v151, v122 offset:64
	ds_bpermute_b32 v199, v151, v122 offset:128
	ds_bpermute_b32 v203, v151, v122 offset:192
	v_exp_f32_e32 v122, v118
	v_fma_f32 v119, -v124, v124, 1.0
	v_max_f32_e32 v119, 0, v119
	v_sqrt_f32_e32 v119, v119
	v_fma_f32 v118, -v122, v122, 1.0
	v_max_f32_e32 v118, 0, v118
	v_sqrt_f32_e32 v118, v118
	v_pk_mul_f32 v[204:205], v[128:129], v[138:139]
	v_add_f32_e32 v66, v187, v66
	v_fmac_f32_e32 v205, v204, v141
	v_pk_mul_f32 v[114:115], v[114:115], v[118:119]
	ds_bpermute_b32 v125, v151, v205
	v_pk_mul_f32 v[110:111], v[114:115], v[110:111]
	v_add_f32_e32 v114, v171, v120
	v_mul_f32_e32 v114, 0xbfb8aa3b, v114
	v_exp_f32_e32 v114, v114
	v_fmac_f32_e32 v111, v124, v110
	ds_bpermute_b32 v129, v151, v205 offset:64
	ds_bpermute_b32 v201, v151, v205 offset:128
	v_add_f32_e32 v114, 1.0, v114
	v_rcp_f32_e32 v115, v114
	v_add_f32_e32 v114, v175, v116
	v_mul_f32_e32 v114, 0xbfb8aa3b, v114
	v_exp_f32_e32 v114, v114
	v_mul_f32_e32 v115, v177, v115
	v_exp_f32_e32 v119, v115
	v_add_f32_e32 v115, v171, v121
	v_mul_f32_e32 v115, 0xbfb8aa3b, v115
	v_exp_f32_e32 v115, v115
	v_fma_f32 v110, -v119, v119, 1.0
	v_add_f32_e32 v114, 1.0, v114
	v_max_f32_e32 v110, 0, v110
	v_add_f32_e32 v115, 1.0, v115
	v_rcp_f32_e32 v115, v115
	v_rcp_f32_e32 v114, v114
	v_sqrt_f32_e32 v118, v110
	v_add_f32_e32 v116, v175, v117
	v_mul_f32_e32 v115, v177, v115
	v_exp_f32_e32 v121, v115
	v_mov_b32_e32 v115, v111
	v_pk_mul_f32 v[110:111], v[114:115], v[118:119]
	v_exp_f32_e32 v114, v106
	v_exp_f32_e32 v115, v107
	v_mul_f32_e32 v116, 0xbfb8aa3b, v116
	v_exp_f32_e32 v116, v116
	v_fma_f32 v106, -v114, v114, 1.0
	v_fma_f32 v107, -v115, v115, 1.0
	v_max_f32_e32 v106, 0, v106
	v_max_f32_e32 v107, 0, v107
	v_sqrt_f32_e32 v106, v106
	v_sqrt_f32_e32 v107, v107
	v_fmac_f32_e32 v111, v110, v112
	v_fma_f32 v110, -v121, v121, 1.0
	v_add_f32_e32 v116, 1.0, v116
	v_max_f32_e32 v110, 0, v110
	v_rcp_f32_e32 v116, v116
	v_sqrt_f32_e32 v120, v110
	v_pk_mul_f32 v[102:103], v[102:103], v[106:107]
	v_add_f32_e32 v106, v178, v108
	v_mul_f32_e32 v106, 0xbfb8aa3b, v106
	v_mov_b32_e32 v117, v111
	v_exp_f32_e32 v106, v106
	v_pk_mul_f32 v[110:111], v[116:117], v[120:121]
	ds_bpermute_b32 v205, v151, v205 offset:192
	v_fmac_f32_e32 v111, v110, v113
	v_mul_f32_e32 v110, v124, v122
	v_mul_f32_e32 v110, v119, v110
	v_mul_f32_e32 v110, v121, v110
	v_add_f32_e32 v106, 1.0, v106
	ds_bpermute_b32 v122, v151, v110
	ds_bpermute_b32 v126, v151, v110 offset:64
	ds_bpermute_b32 v198, v151, v110 offset:128
	ds_bpermute_b32 v202, v151, v110 offset:192
	v_rcp_f32_e32 v106, v106
	ds_bpermute_b32 v124, v151, v111
	ds_bpermute_b32 v128, v151, v111 offset:64
	ds_bpermute_b32 v200, v151, v111 offset:128
	ds_bpermute_b32 v204, v151, v111 offset:192
	v_mul_f32_e32 v106, v182, v106
	s_waitcnt lgkmcnt(6)
	v_pk_mul_f32 v[110:111], v[122:123], v[126:127]
	s_waitcnt lgkmcnt(4)
	v_pk_mul_f32 v[112:113], v[198:199], v[202:203]
	v_exp_f32_e32 v107, v106
	v_add_f32_e32 v106, v178, v109
	v_pk_mul_f32 v[110:111], v[110:111], v[112:113]
	s_waitcnt lgkmcnt(3)
	v_pk_fma_f32 v[112:113], v[172:173], v[122:123], v[124:125]
	v_mul_f32_e32 v106, 0xbfb8aa3b, v106
	s_waitcnt lgkmcnt(2)
	v_pk_fma_f32 v[112:113], v[112:113], v[126:127], v[128:129]
	v_exp_f32_e32 v106, v106
	s_waitcnt lgkmcnt(1)
	v_pk_fma_f32 v[112:113], v[112:113], v[198:199], v[200:201]
	v_pk_mul_f32 v[162:163], v[162:163], v[110:111]
	s_waitcnt lgkmcnt(0)
; __device__ __forceinline__ float fsig2(float x) { return __builtin_amdgcn_rcpf(1.0f + __builtin_amdgcn_exp2f(-LOG2E * x)); }
; template <int PASS> __device__ __forceinline__ void lru_wave_item(LAS unsigned char* lds, LAS unsigned char* vw, int b, int c, int h, const MixP& p, int lane, float (&Hrun)[8], bool cont) {
;     ...
;         for (int n = 0; n < 8; ++n) {
;             const f32x4 aVn = __builtin_amdgcn_mfma_f32_16x16x32_bf16(af[n >> 1], idf[n & 1], (f32x4){0.f, 0.f, 0.f, 0.f}, 0, 0, 0);
;             float av[4], bxv[4];
; #pragma unroll
;             for (int j = 0; j < 4; ++j) {
;                 const float r = fsig2(aR[n][j] + pba[n]), ig = fsig2(aI[n][j] + pbx[n]);
;                 const float a = __builtin_amdgcn_exp2f(r * pk8[n]), mult = __builtin_amdgcn_sqrtf(fmaxf(1.0f - a * a, 0.f));
;                 av[j] = a; bxv[j] = mult * ig * aVn[j];
;             }
;             const float H0 = bxv[0], H1 = av[1] * H0 + bxv[1], H2 = av[2] * H1 + bxv[2], H3 = av[3] * H2 + bxv[3];
;             const float A0 = av[0], A1 = av[1] * A0, A2 = av[2] * A1, A3 = av[3] * A2;
;             float At[4], Ht[4];
; #pragma unroll
;             for (int q = 0; q < 4; ++q) { At[q] = __shfl(A3, fr + 16 * q); Ht[q] = __shfl(H3, fr + 16 * q); }
;             const float c0 = Hrun[n], c1 = At[0] * c0 + Ht[0], c2 = At[1] * c1 + Ht[1], c3 = At[2] * c2 + Ht[2], c4 = At[3] * c3 + Ht[3];
;             Hrun[n] = c4;
;             if (PASS == 1) Arun[n] *= (At[0] * At[1]) * (At[2] * At[3]);
	v_pk_fma_f32 v[172:173], v[112:113], v[202:203], v[204:205]
	v_mfma_f32_16x16x32_bf16 v[110:113], v[82:85], v[2:5], 0
	v_add_f32_e32 v106, 1.0, v106
	v_rcp_f32_e32 v106, v106
	v_rcp_f32_e32 v108, v105
	v_mfma_f32_16x16x32_bf16 v[82:85], v[82:85], v[6:9], 0
	v_mul_f32_e32 v70, v189, v70
	s_nop 2
	v_pk_mul_f32 v[102:103], v[102:103], v[110:111]
	v_mul_f32_e32 v105, v182, v106
	v_fmac_f32_e32 v103, v115, v102
	v_fma_f32 v102, -v107, v107, 1.0
	v_max_f32_e32 v102, 0, v102
	v_sqrt_f32_e32 v106, v102
	v_exp_f32_e32 v111, v105
	v_mov_b32_e32 v105, v103
	v_add_f32_e32 v67, v187, v67
	v_pk_mul_f32 v[102:103], v[104:105], v[106:107]
	v_mul_f32_e32 v71, v189, v71
	v_fmac_f32_e32 v103, v102, v112
	v_fma_f32 v102, -v111, v111, 1.0
	v_max_f32_e32 v102, 0, v102
	v_sqrt_f32_e32 v110, v102
	v_mov_b32_e32 v109, v103
	v_mul_f32_e32 v66, 0xbfb8aa3b, v66
	v_mul_f32_e32 v67, 0xbfb8aa3b, v67
	v_pk_mul_f32 v[102:103], v[108:109], v[110:111]
	v_exp_f32_e32 v66, v66
	v_fmac_f32_e32 v103, v102, v113
	v_mul_f32_e32 v102, v115, v114
	v_mul_f32_e32 v102, v107, v102
	v_mul_f32_e32 v105, v111, v102
	ds_bpermute_b32 v102, v151, v105
	ds_bpermute_b32 v104, v151, v103
	ds_bpermute_b32 v106, v151, v105 offset:64
	ds_bpermute_b32 v108, v151, v103 offset:64
	ds_bpermute_b32 v110, v151, v105 offset:128
	ds_bpermute_b32 v112, v151, v103 offset:128
	ds_bpermute_b32 v114, v151, v105 offset:192
	ds_bpermute_b32 v116, v151, v103 offset:192
	v_exp_f32_e32 v103, v90
	v_exp_f32_e32 v105, v91
	v_exp_f32_e32 v67, v67
	v_add_f32_e32 v66, 1.0, v66
	v_fma_f32 v90, -v103, v103, 1.0
	v_fma_f32 v91, -v105, v105, 1.0
	v_max_f32_e32 v90, 0, v90
	v_max_f32_e32 v91, 0, v91
	v_sqrt_f32_e32 v90, v90
	v_sqrt_f32_e32 v91, v91
	v_add_f32_e32 v67, 1.0, v67
	v_rcp_f32_e32 v66, v66
	v_rcp_f32_e32 v67, v67
	v_pk_mul_f32 v[86:87], v[86:87], v[90:91]
	v_add_f32_e32 v62, v190, v62
	v_pk_mul_f32 v[82:83], v[86:87], v[82:83]
	v_add_f32_e32 v86, v179, v92
	v_mul_f32_e32 v86, 0xbfb8aa3b, v86
	v_exp_f32_e32 v86, v86
	v_fmac_f32_e32 v83, v105, v82
	v_add_f32_e32 v63, v190, v63
	v_mul_f32_e32 v62, 0xbfb8aa3b, v62
	v_add_f32_e32 v86, 1.0, v86
	v_rcp_f32_e32 v87, v86
	v_add_f32_e32 v86, v181, v88
	v_mul_f32_e32 v86, 0xbfb8aa3b, v86
	v_exp_f32_e32 v86, v86
	v_mul_f32_e32 v87, v183, v87
	v_exp_f32_e32 v91, v87
	v_add_f32_e32 v87, v179, v93
	v_mul_f32_e32 v87, 0xbfb8aa3b, v87
	v_exp_f32_e32 v87, v87
	v_fma_f32 v82, -v91, v91, 1.0
	v_add_f32_e32 v86, 1.0, v86
	v_max_f32_e32 v82, 0, v82
	v_add_f32_e32 v87, 1.0, v87
	v_rcp_f32_e32 v87, v87
	v_rcp_f32_e32 v86, v86
	v_sqrt_f32_e32 v90, v82
	v_add_f32_e32 v88, v181, v89
	v_mul_f32_e32 v87, v183, v87
	v_exp_f32_e32 v93, v87
	v_mov_b32_e32 v87, v83
	v_pk_mul_f32 v[82:83], v[86:87], v[90:91]
	v_exp_f32_e32 v86, v78
	v_exp_f32_e32 v87, v79
	v_mul_f32_e32 v88, 0xbfb8aa3b, v88
	v_exp_f32_e32 v88, v88
	v_fma_f32 v78, -v86, v86, 1.0
	v_fma_f32 v79, -v87, v87, 1.0
	v_max_f32_e32 v78, 0, v78
	v_max_f32_e32 v79, 0, v79
	v_sqrt_f32_e32 v78, v78
	v_sqrt_f32_e32 v79, v79
	v_fmac_f32_e32 v83, v82, v84
	v_fma_f32 v82, -v93, v93, 1.0
	v_add_f32_e32 v88, 1.0, v88
	v_max_f32_e32 v82, 0, v82
	v_rcp_f32_e32 v88, v88
	v_sqrt_f32_e32 v92, v82
	v_pk_mul_f32 v[74:75], v[74:75], v[78:79]
	v_add_f32_e32 v78, v184, v80
	v_mul_f32_e32 v78, 0xbfb8aa3b, v78
	v_mov_b32_e32 v89, v83
	v_exp_f32_e32 v78, v78
	v_pk_mul_f32 v[82:83], v[88:89], v[92:93]
	v_rcp_f32_e32 v80, v77
	v_fmac_f32_e32 v83, v82, v85
	v_mul_f32_e32 v82, v105, v103
	v_mul_f32_e32 v82, v91, v82
	v_mul_f32_e32 v82, v93, v82
	v_add_f32_e32 v78, 1.0, v78
	ds_bpermute_b32 v103, v151, v82
	ds_bpermute_b32 v107, v151, v82 offset:64
	ds_bpermute_b32 v111, v151, v82 offset:128
	ds_bpermute_b32 v115, v151, v82 offset:192
	v_rcp_f32_e32 v78, v78
	ds_bpermute_b32 v105, v151, v83
	ds_bpermute_b32 v109, v151, v83 offset:64
	ds_bpermute_b32 v113, v151, v83 offset:128
	ds_bpermute_b32 v117, v151, v83 offset:192
	v_mul_f32_e32 v78, v188, v78
	s_waitcnt lgkmcnt(6)
	v_pk_mul_f32 v[82:83], v[102:103], v[106:107]
	s_waitcnt lgkmcnt(4)
	v_pk_mul_f32 v[84:85], v[110:111], v[114:115]
	v_exp_f32_e32 v79, v78
	v_add_f32_e32 v78, v184, v81
	v_pk_mul_f32 v[82:83], v[82:83], v[84:85]
	s_waitcnt lgkmcnt(3)
	v_pk_fma_f32 v[84:85], v[166:167], v[102:103], v[104:105]
	v_mul_f32_e32 v78, 0xbfb8aa3b, v78
	s_waitcnt lgkmcnt(2)
	v_pk_fma_f32 v[84:85], v[84:85], v[106:107], v[108:109]
	v_exp_f32_e32 v78, v78
	s_waitcnt lgkmcnt(1)
	v_pk_fma_f32 v[84:85], v[84:85], v[110:111], v[112:113]
	v_pk_mul_f32 v[168:169], v[168:169], v[82:83]
	s_waitcnt lgkmcnt(0)
; __device__ __forceinline__ float fsig2(float x) { return __builtin_amdgcn_rcpf(1.0f + __builtin_amdgcn_exp2f(-LOG2E * x)); }
; template <int PASS> __device__ __forceinline__ void lru_wave_item(LAS unsigned char* lds, LAS unsigned char* vw, int b, int c, int h, const MixP& p, int lane, float (&Hrun)[8], bool cont) {
;     ...
;         for (int n = 0; n < 8; ++n) {
;             const f32x4 aVn = __builtin_amdgcn_mfma_f32_16x16x32_bf16(af[n >> 1], idf[n & 1], (f32x4){0.f, 0.f, 0.f, 0.f}, 0, 0, 0);
;             float av[4], bxv[4];
; #pragma unroll
;             for (int j = 0; j < 4; ++j) {
;                 const float r = fsig2(aR[n][j] + pba[n]), ig = fsig2(aI[n][j] + pbx[n]);
;                 const float a = __builtin_amdgcn_exp2f(r * pk8[n]), mult = __builtin_amdgcn_sqrtf(fmaxf(1.0f - a * a, 0.f));
;                 av[j] = a; bxv[j] = mult * ig * aVn[j];
;             }
;             const float H0 = bxv[0], H1 = av[1] * H0 + bxv[1], H2 = av[2] * H1 + bxv[2], H3 = av[3] * H2 + bxv[3];
;             const float A0 = av[0], A1 = av[1] * A0, A2 = av[2] * A1, A3 = av[3] * A2;
;             float At[4], Ht[4];
; #pragma unroll
;             for (int q = 0; q < 4; ++q) { At[q] = __shfl(A3, fr + 16 * q); Ht[q] = __shfl(H3, fr + 16 * q); }
;             const float c0 = Hrun[n], c1 = At[0] * c0 + Ht[0], c2 = At[1] * c1 + Ht[1], c3 = At[2] * c2 + Ht[2], c4 = At[3] * c3 + Ht[3];
;             Hrun[n] = c4;
;             if (PASS == 1) Arun[n] *= (At[0] * At[1]) * (At[2] * At[3]);
	v_pk_fma_f32 v[166:167], v[84:85], v[114:115], v[116:117]
	v_mfma_f32_16x16x32_bf16 v[82:85], v[54:57], v[2:5], 0
	v_add_f32_e32 v78, 1.0, v78
	v_rcp_f32_e32 v78, v78
	v_mul_f32_e32 v63, 0xbfb8aa3b, v63
	v_mfma_f32_16x16x32_bf16 v[54:57], v[54:57], v[6:9], 0
	v_exp_f32_e32 v62, v62
	s_nop 2
	v_pk_mul_f32 v[74:75], v[74:75], v[82:83]
	v_mul_f32_e32 v77, v188, v78
	v_fmac_f32_e32 v75, v87, v74
	v_fma_f32 v74, -v79, v79, 1.0
	v_max_f32_e32 v74, 0, v74
	v_sqrt_f32_e32 v78, v74
	v_exp_f32_e32 v83, v77
	v_mov_b32_e32 v77, v75
	v_exp_f32_e32 v63, v63
	v_pk_mul_f32 v[74:75], v[76:77], v[78:79]
	v_add_f32_e32 v62, 1.0, v62
	v_fmac_f32_e32 v75, v74, v84
	v_fma_f32 v74, -v83, v83, 1.0
	v_max_f32_e32 v74, 0, v74
	v_sqrt_f32_e32 v82, v74
	v_mov_b32_e32 v81, v75
	v_add_f32_e32 v63, 1.0, v63
	v_rcp_f32_e32 v62, v62
	v_pk_mul_f32 v[74:75], v[80:81], v[82:83]
	v_rcp_f32_e32 v63, v63
	v_fmac_f32_e32 v75, v74, v85
	v_mul_f32_e32 v74, v87, v86
	v_mul_f32_e32 v74, v79, v74
	v_mul_f32_e32 v77, v83, v74
	ds_bpermute_b32 v74, v151, v77
	ds_bpermute_b32 v76, v151, v75
	ds_bpermute_b32 v78, v151, v77 offset:64
	ds_bpermute_b32 v80, v151, v75 offset:64
	ds_bpermute_b32 v82, v151, v77 offset:128
	ds_bpermute_b32 v84, v151, v75 offset:128
	ds_bpermute_b32 v86, v151, v77 offset:192
	ds_bpermute_b32 v88, v151, v75 offset:192
	v_exp_f32_e32 v75, v70
	v_exp_f32_e32 v77, v71
	v_add_f32_e32 v58, v192, v58
	v_mul_f32_e32 v62, v194, v62
	v_fma_f32 v70, -v75, v75, 1.0
	v_fma_f32 v71, -v77, v77, 1.0
	v_max_f32_e32 v70, 0, v70
	v_max_f32_e32 v71, 0, v71
	v_sqrt_f32_e32 v70, v70
	v_sqrt_f32_e32 v71, v71
	v_add_f32_e32 v59, v192, v59
	v_mul_f32_e32 v63, v194, v63
	v_mul_f32_e32 v58, 0xbfb8aa3b, v58
	v_pk_mul_f32 v[66:67], v[66:67], v[70:71]
	v_mul_f32_e32 v59, 0xbfb8aa3b, v59
	v_pk_mul_f32 v[54:55], v[66:67], v[54:55]
	v_add_f32_e32 v66, v185, v72
	v_mul_f32_e32 v66, 0xbfb8aa3b, v66
	v_exp_f32_e32 v66, v66
	v_fmac_f32_e32 v55, v77, v54
	v_exp_f32_e32 v58, v58
	v_exp_f32_e32 v59, v59
	v_add_f32_e32 v66, 1.0, v66
	v_rcp_f32_e32 v67, v66
	v_add_f32_e32 v66, v187, v68
	v_mul_f32_e32 v66, 0xbfb8aa3b, v66
	v_exp_f32_e32 v66, v66
	v_mul_f32_e32 v67, v189, v67
	v_exp_f32_e32 v71, v67
	v_add_f32_e32 v67, v185, v73
	v_mul_f32_e32 v67, 0xbfb8aa3b, v67
	v_exp_f32_e32 v67, v67
	v_fma_f32 v54, -v71, v71, 1.0
	v_add_f32_e32 v66, 1.0, v66
	v_max_f32_e32 v54, 0, v54
	v_add_f32_e32 v67, 1.0, v67
	v_rcp_f32_e32 v67, v67
	v_rcp_f32_e32 v66, v66
	v_add_f32_e32 v68, v187, v69
	v_sqrt_f32_e32 v70, v54
	v_mul_f32_e32 v67, v189, v67
	v_mul_f32_e32 v68, 0xbfb8aa3b, v68
	v_exp_f32_e32 v73, v67
	v_exp_f32_e32 v68, v68
	v_mov_b32_e32 v67, v55
	v_pk_mul_f32 v[54:55], v[66:67], v[70:71]
	v_exp_f32_e32 v66, v62
	v_fmac_f32_e32 v55, v54, v56
	v_fma_f32 v54, -v73, v73, 1.0
	v_add_f32_e32 v68, 1.0, v68
	v_max_f32_e32 v54, 0, v54
	v_rcp_f32_e32 v68, v68
	v_sqrt_f32_e32 v72, v54
	v_mov_b32_e32 v69, v55
	v_exp_f32_e32 v67, v63
	v_fma_f32 v62, -v66, v66, 1.0
	v_pk_mul_f32 v[54:55], v[68:69], v[72:73]
	v_add_f32_e32 v58, 1.0, v58
	v_fmac_f32_e32 v55, v54, v57
	v_mul_f32_e32 v54, v77, v75
	v_mul_f32_e32 v54, v71, v54
	v_mul_f32_e32 v54, v73, v54
	ds_bpermute_b32 v75, v151, v54
	ds_bpermute_b32 v79, v151, v54 offset:64
	ds_bpermute_b32 v83, v151, v54 offset:128
	ds_bpermute_b32 v87, v151, v54 offset:192
	ds_bpermute_b32 v77, v151, v55
	ds_bpermute_b32 v81, v151, v55 offset:64
	ds_bpermute_b32 v85, v151, v55 offset:128
	ds_bpermute_b32 v89, v151, v55 offset:192
	s_waitcnt lgkmcnt(6)
	v_pk_mul_f32 v[54:55], v[74:75], v[78:79]
	s_waitcnt lgkmcnt(4)
	v_pk_mul_f32 v[56:57], v[82:83], v[86:87]
	v_fma_f32 v63, -v67, v67, 1.0
	v_pk_mul_f32 v[54:55], v[54:55], v[56:57]
	s_waitcnt lgkmcnt(3)
	v_pk_fma_f32 v[56:57], v[160:161], v[74:75], v[76:77]
	v_max_f32_e32 v62, 0, v62
	s_waitcnt lgkmcnt(2)
	v_pk_fma_f32 v[56:57], v[56:57], v[78:79], v[80:81]
	v_add_f32_e32 v59, 1.0, v59
	v_max_f32_e32 v63, 0, v63
	s_waitcnt lgkmcnt(1)
	v_pk_fma_f32 v[56:57], v[56:57], v[82:83], v[84:85]
	v_rcp_f32_e32 v58, v58
	v_sqrt_f32_e32 v62, v62
	v_rcp_f32_e32 v59, v59
	v_sqrt_f32_e32 v63, v63
	s_waitcnt lgkmcnt(0)
; __device__ __forceinline__ float fsig2(float x) { return __builtin_amdgcn_rcpf(1.0f + __builtin_amdgcn_exp2f(-LOG2E * x)); }
; template <int PASS> __device__ __forceinline__ void lru_wave_item(LAS unsigned char* lds, LAS unsigned char* vw, int b, int c, int h, const MixP& p, int lane, float (&Hrun)[8], bool cont) {
;     ...
;         for (int n = 0; n < 8; ++n) {
;             const f32x4 aVn = __builtin_amdgcn_mfma_f32_16x16x32_bf16(af[n >> 1], idf[n & 1], (f32x4){0.f, 0.f, 0.f, 0.f}, 0, 0, 0);
;             float av[4], bxv[4];
; #pragma unroll
;             for (int j = 0; j < 4; ++j) {
;                 const float r = fsig2(aR[n][j] + pba[n]), ig = fsig2(aI[n][j] + pbx[n]);
;                 const float a = __builtin_amdgcn_exp2f(r * pk8[n]), mult = __builtin_amdgcn_sqrtf(fmaxf(1.0f - a * a, 0.f));
;                 av[j] = a; bxv[j] = mult * ig * aVn[j];
;             }
;             const float H0 = bxv[0], H1 = av[1] * H0 + bxv[1], H2 = av[2] * H1 + bxv[2], H3 = av[3] * H2 + bxv[3];
;             const float A0 = av[0], A1 = av[1] * A0, A2 = av[2] * A1, A3 = av[3] * A2;
;             float At[4], Ht[4];
; #pragma unroll
;             for (int q = 0; q < 4; ++q) { At[q] = __shfl(A3, fr + 16 * q); Ht[q] = __shfl(H3, fr + 16 * q); }
;             const float c0 = Hrun[n], c1 = At[0] * c0 + Ht[0], c2 = At[1] * c1 + Ht[1], c3 = At[2] * c2 + Ht[2], c4 = At[3] * c3 + Ht[3];
;             Hrun[n] = c4;
;             if (PASS == 1) Arun[n] *= (At[0] * At[1]) * (At[2] * At[3]);
;     ...
;     if (PASS == 1 && fq == 0) {
; #pragma unroll
;         for (int n = 0; n < 8; ++n) *(f32x2*)(p.summ + (((size_t)b * NCH + c) * LW + h * 128 + 16 * n + fr) * 2) = (f32x2){Arun[n], Hrun[n]};
;     }
	v_pk_fma_f32 v[160:161], v[56:57], v[86:87], v[88:89]
	v_pk_mul_f32 v[164:165], v[164:165], v[54:55]
	v_mfma_f32_16x16x32_bf16 v[54:57], v[50:53], v[2:5], 0
	v_mul_f32_e64 v58, v58, v62
	v_mul_f32_e64 v59, v59, v63
	v_mfma_f32_16x16x32_bf16 v[50:53], v[50:53], v[6:9], 0
	s_nop 4
	v_mul_f32_e64 v54, v58, v54
	v_mul_f32_e64 v55, v59, v55
	v_add_f32_e32 v58, v190, v64
	v_mul_f32_e32 v58, 0xbfb8aa3b, v58
	v_exp_f32_e32 v58, v58
	v_fmac_f32_e32 v55, v67, v54
	v_add_f32_e32 v58, 1.0, v58
	v_rcp_f32_e32 v59, v58
	v_add_f32_e32 v58, v192, v60
	v_mul_f32_e32 v58, 0xbfb8aa3b, v58
	v_exp_f32_e32 v58, v58
	v_mul_f32_e32 v59, v194, v59
	v_exp_f32_e32 v63, v59
	v_add_f32_e32 v59, v190, v65
	v_mul_f32_e32 v59, 0xbfb8aa3b, v59
	v_exp_f32_e32 v59, v59
	v_fma_f32 v54, -v63, v63, 1.0
	v_add_f32_e32 v58, 1.0, v58
	v_max_f32_e32 v54, 0, v54
	v_add_f32_e32 v59, 1.0, v59
	v_rcp_f32_e32 v59, v59
	v_rcp_f32_e32 v58, v58
	v_add_f32_e32 v60, v192, v61
	v_sqrt_f32_e32 v62, v54
	v_mul_f32_e32 v59, v194, v59
	v_mul_f32_e32 v60, 0xbfb8aa3b, v60
	v_exp_f32_e32 v65, v59
	v_exp_f32_e32 v60, v60
	v_mov_b32_e32 v59, v55
	v_pk_mul_f32 v[54:55], v[58:59], v[62:63]
	v_add_f32_e32 v59, v193, v95
	v_fmac_f32_e32 v55, v54, v56
	v_fma_f32 v54, -v65, v65, 1.0
	v_add_f32_e32 v60, 1.0, v60
	v_max_f32_e32 v54, 0, v54
	v_rcp_f32_e32 v60, v60
	v_sqrt_f32_e32 v64, v54
	v_mov_b32_e32 v61, v55
	v_mul_f32_e32 v59, 0xbfb8aa3b, v59
	v_exp_f32_e32 v59, v59
	v_pk_mul_f32 v[54:55], v[60:61], v[64:65]
	v_add_f32_e32 v61, v193, v96
	v_fmac_f32_e32 v55, v54, v57
	ds_bpermute_b32 v56, v151, v55
	ds_bpermute_b32 v60, v151, v55 offset:64
	ds_bpermute_b32 v64, v151, v55 offset:128
	ds_bpermute_b32 v68, v151, v55 offset:192
	v_add_f32_e32 v55, v191, v98
	v_mul_f32_e32 v55, 0xbfb8aa3b, v55
	v_exp_f32_e32 v55, v55
	v_mul_f32_e32 v54, v67, v66
	v_mul_f32_e32 v54, v63, v54
	v_mul_f32_e32 v57, v65, v54
	v_add_f32_e32 v55, 1.0, v55
	v_rcp_f32_e32 v55, v55
	ds_bpermute_b32 v54, v151, v57
	ds_bpermute_b32 v58, v151, v57 offset:64
	ds_bpermute_b32 v62, v151, v57 offset:128
	ds_bpermute_b32 v66, v151, v57 offset:192
	v_add_f32_e32 v57, v193, v94
	v_mul_f32_e32 v57, 0xbfb8aa3b, v57
	v_exp_f32_e32 v57, v57
	v_mul_f32_e32 v55, v195, v55
	v_exp_f32_e32 v55, v55
	v_add_f32_e32 v59, 1.0, v59
	v_add_f32_e32 v57, 1.0, v57
	v_rcp_f32_e32 v70, v57
	v_fma_f32 v57, -v55, v55, 1.0
	v_max_f32_e32 v57, 0, v57
	v_sqrt_f32_e32 v72, v57
	v_add_f32_e32 v57, v191, v99
	v_mul_f32_e32 v57, 0xbfb8aa3b, v57
	v_exp_f32_e32 v57, v57
	v_rcp_f32_e32 v71, v59
	v_mul_f32_e32 v61, 0xbfb8aa3b, v61
	v_exp_f32_e32 v61, v61
	v_add_f32_e32 v57, 1.0, v57
	v_rcp_f32_e32 v57, v57
	v_add_f32_e32 v61, 1.0, v61
	v_mul_f32_e32 v57, v195, v57
	v_exp_f32_e32 v57, v57
	s_nop 0
	v_fma_f32 v59, -v57, v57, 1.0
	v_max_f32_e32 v59, 0, v59
	v_sqrt_f32_e32 v73, v59
	v_add_f32_e32 v59, v191, v100
	v_mul_f32_e32 v59, 0xbfb8aa3b, v59
	v_exp_f32_e32 v59, v59
	v_pk_mul_f32 v[70:71], v[70:71], v[72:73]
	v_add_f32_e32 v59, 1.0, v59
	v_rcp_f32_e32 v59, v59
	v_pk_mul_f32 v[50:51], v[70:71], v[50:51]
	v_rcp_f32_e32 v70, v61
	v_fmac_f32_e32 v51, v57, v50
	v_mul_f32_e32 v59, v195, v59
	v_exp_f32_e32 v73, v59
	v_add_f32_e32 v59, v191, v101
	v_mul_f32_e32 v59, 0xbfb8aa3b, v59
	v_exp_f32_e32 v59, v59
	v_fma_f32 v50, -v73, v73, 1.0
	v_max_f32_e32 v50, 0, v50
	v_add_f32_e32 v61, v193, v97
	v_add_f32_e32 v59, 1.0, v59
	v_rcp_f32_e32 v59, v59
	v_sqrt_f32_e32 v72, v50
	v_mul_f32_e32 v61, 0xbfb8aa3b, v61
	v_exp_f32_e32 v61, v61
	v_mul_f32_e32 v59, v195, v59
	v_exp_f32_e32 v77, v59
	v_mov_b32_e32 v71, v51
	v_pk_mul_f32 v[50:51], v[70:71], v[72:73]
	v_add_f32_e32 v61, 1.0, v61
	v_fmac_f32_e32 v51, v50, v52
	v_fma_f32 v50, -v77, v77, 1.0
	v_max_f32_e32 v50, 0, v50
	v_rcp_f32_e32 v74, v61
	v_sqrt_f32_e32 v76, v50
	v_mov_b32_e32 v75, v51
	v_pk_mul_f32 v[50:51], v[74:75], v[76:77]
	s_nop 0
	v_fmac_f32_e32 v51, v50, v53
	v_mul_f32_e32 v50, v57, v55
	v_mul_f32_e32 v50, v73, v50
	v_mul_f32_e32 v50, v77, v50
	ds_bpermute_b32 v55, v151, v50
	ds_bpermute_b32 v59, v151, v50 offset:64
	ds_bpermute_b32 v63, v151, v50 offset:128
	ds_bpermute_b32 v67, v151, v50 offset:192
	ds_bpermute_b32 v57, v151, v51
	ds_bpermute_b32 v61, v151, v51 offset:64
	ds_bpermute_b32 v65, v151, v51 offset:128
	ds_bpermute_b32 v69, v151, v51 offset:192
	s_waitcnt lgkmcnt(6)
	v_pk_mul_f32 v[50:51], v[54:55], v[58:59]
	s_waitcnt lgkmcnt(4)
	v_pk_mul_f32 v[52:53], v[62:63], v[66:67]
	s_nop 0
	v_pk_mul_f32 v[50:51], v[50:51], v[52:53]
	s_waitcnt lgkmcnt(3)
	v_pk_fma_f32 v[52:53], v[156:157], v[54:55], v[56:57]
	v_pk_mul_f32 v[158:159], v[158:159], v[50:51]
	s_waitcnt lgkmcnt(2)
	v_pk_fma_f32 v[52:53], v[52:53], v[58:59], v[60:61]
	s_waitcnt lgkmcnt(1)
	v_pk_fma_f32 v[52:53], v[52:53], v[62:63], v[64:65]
	s_waitcnt lgkmcnt(0)
	v_pk_fma_f32 v[156:157], v[52:53], v[66:67], v[68:69]
	s_cbranch_vccz .LBB0_668
	s_and_saveexec_b64 s[28:29], s[4:5]
	s_cbranch_execz .LBB0_666
	s_ashr_i32 s59, s58, 31
	s_lshl_b64 s[16:17], s[58:59], 6
	s_ashr_i32 s2, s11, 31
	s_add_u32 s3, s16, s11
	s_addc_u32 s2, s17, s2
	s_mulk_i32 s2, 0x500
	v_mad_u64_u32 v[10:11], s[16:17], s3, v217, v[152:153]
	v_add_u32_e32 v11, s2, v11
	v_mov_b32_e32 v12, v163
	v_mov_b32_e32 v13, v173
	v_lshl_add_u64 v[10:11], v[10:11], 3, s[94:95]
	global_store_dwordx2 v[10:11], v[12:13], off
	v_mov_b32_e32 v12, v168
	v_mov_b32_e32 v13, v166
	global_store_dwordx2 v[10:11], v[12:13], off offset:256
	v_mov_b32_e32 v12, v164
	v_mov_b32_e32 v13, v160
	v_mov_b32_e32 v163, v172
	v_mov_b32_e32 v166, v169
	global_store_dwordx2 v[10:11], v[12:13], off offset:512
	v_mov_b32_e32 v160, v165
	v_mov_b32_e32 v12, v158
	v_mov_b32_e32 v13, v156
	v_mov_b32_e32 v156, v159
	global_store_dwordx2 v[10:11], v[162:163], off offset:128
	global_store_dwordx2 v[10:11], v[166:167], off offset:384
	global_store_dwordx2 v[10:11], v[160:161], off offset:640
	global_store_dwordx2 v[10:11], v[12:13], off offset:768
	global_store_dwordx2 v[10:11], v[156:157], off offset:896
	s_branch .LBB0_666

; __device__ __forceinline__ float bflo(unsigned w) { return __uint_as_float(w << 16); }
; __device__ __forceinline__ float bfhi(unsigned w) { return __uint_as_float(w & 0xffff0000u); }
; template <int PASS> __device__ __forceinline__ void lru_wave_item(LAS unsigned char* lds, LAS unsigned char* vw, int b, int c, int h, const MixP& p, int lane, float (&Hrun)[8], bool cont) {
;     ...
;     for (int st = 0; st < CT / 16; ++st) {
;         const int s0 = c * CT + 16 * st;
;         u32x4 ur[7];
;         {
;             const int sb = s0 + 4 * fq - 3;
; #pragma unroll
;             for (int r = 0; r < 7; ++r) ur[r] = *(const u32x4*)(ub + (size_t)max(sb + r, 0) * P1W);
;         }
;         if (s0 == 0 && fq == 0) {
; #pragma unroll
;             for (int r = 0; r < 3; ++r) ur[r] = (u32x4){0u, 0u, 0u, 0u};
;         }
; #pragma unroll
;         for (int jj = 0; jj < 4; ++jj) {
;             f32x2 o[4] = {bv[0], bv[1], bv[2], bv[3]};
; #pragma unroll
;             for (int k = 0; k < 4; ++k) { const u32x4 uk = ur[jj + k];
;                 o[0] = wv[k][0] * (f32x2){bflo(uk.x), bfhi(uk.x)} + o[0]; o[1] = wv[k][1] * (f32x2){bflo(uk.y), bfhi(uk.y)} + o[1];
;                 o[2] = wv[k][2] * (f32x2){bflo(uk.z), bfhi(uk.z)} + o[2]; o[3] = wv[k][3] * (f32x2){bflo(uk.w), bfhi(uk.w)} + o[3]; }
;     ...
;                 const u32x4 g = *(const u32x4*)(p.P2 + row * P2W + h * 128 + cg * 8);
.LBB0_818:
	s_or_b32 s22, s19, s11
	v_add_u32_e32 v0, s22, v224
	v_max_i32_e32 v2, 0, v0
	v_mad_u64_u32 v[2:3], s[20:21], v2, s82, v[182:183]
	global_load_dwordx4 v[74:77], v[2:3], off offset:1024
	v_max_i32_e32 v2, -1, v0
	v_add_u32_e32 v2, 1, v2
	v_mad_u64_u32 v[2:3], s[20:21], v2, s82, v[182:183]
	global_load_dwordx4 v[78:81], v[2:3], off offset:1024
	v_or_b32_e32 v2, 2, v0
	v_max_i32_e32 v2, 0, v2
	v_mad_u64_u32 v[2:3], s[20:21], v2, s82, v[182:183]
	global_load_dwordx4 v[82:85], v[2:3], off offset:1024
	v_or_b32_e32 v2, s22, v223
	v_max_i32_e32 v2, 0, v2
	v_mad_u64_u32 v[2:3], s[20:21], v2, s82, v[182:183]
	global_load_dwordx4 v[70:73], v[2:3], off offset:1024
	v_max_i32_e32 v2, -4, v0
	v_add_u32_e32 v2, 4, v2
	v_mad_u64_u32 v[2:3], s[20:21], v2, s82, v[182:183]
	global_load_dwordx4 v[66:69], v[2:3], off offset:1024
	v_max_i32_e32 v2, -5, v0
	v_add_u32_e32 v2, 5, v2
	v_mad_u64_u32 v[2:3], s[20:21], v2, s82, v[182:183]
	global_load_dwordx4 v[6:9], v[2:3], off offset:1024
	v_max_i32_e32 v0, -6, v0
	v_add_u32_e32 v0, 6, v0
	v_mad_u64_u32 v[2:3], s[20:21], v0, s82, v[182:183]
	global_load_dwordx4 v[2:5], v[2:3], off offset:1024
	s_cmp_eq_u32 s22, 0
	s_cselect_b64 s[20:21], -1, 0
	s_and_b64 s[20:21], s[20:21], s[4:5]
	s_or_b32 s19, s19, s18
	s_and_b64 vcc, exec, s[12:13]
	s_mov_b64 s[12:13], 0
	v_or_b32_e32 v96, s19, v203
	v_mad_i64_i32 v[240:241], s[98:99], v96, s83, v[152:153]
	global_load_dwordx4 v[240:243], v[240:241], off
	v_or_b32_e32 v96, s19, v225
	v_mad_i64_i32 v[244:245], s[98:99], v96, s83, v[152:153]
	global_load_dwordx4 v[244:247], v[244:245], off
	v_or_b32_e32 v96, s19, v226
	v_mad_i64_i32 v[248:249], s[98:99], v96, s83, v[152:153]
	global_load_dwordx4 v[248:251], v[248:249], off
	v_or_b32_e32 v96, s19, v227
	v_mad_i64_i32 v[206:207], s[98:99], v96, s83, v[152:153]
	global_load_dwordx2 v[210:211], v[206:207], off offset:8
	global_load_dwordx2 v[206:207], v[206:207], off
	s_add_i32 s100, s22, 16
	v_add_u32_e32 v96, s100, v224
	v_max_i32_e32 v97, 0, v96
	v_mad_u64_u32 v[98:99], s[98:99], v97, s82, v[182:183]
	global_load_dword v237, v[98:99], off offset:1024
	v_add_u32_e32 v97, 1, v96
	v_max_i32_e32 v97, 0, v97
	v_mad_u64_u32 v[98:99], s[98:99], v97, s82, v[182:183]
	global_load_dword v237, v[98:99], off offset:1024
	v_add_u32_e32 v97, 2, v96
	v_max_i32_e32 v97, 0, v97
	v_mad_u64_u32 v[98:99], s[98:99], v97, s82, v[182:183]
	global_load_dword v237, v[98:99], off offset:1024
	v_add_u32_e32 v97, 3, v96
	v_max_i32_e32 v97, 0, v97
	v_mad_u64_u32 v[98:99], s[98:99], v97, s82, v[182:183]
	global_load_dword v237, v[98:99], off offset:1024
	v_add_u32_e32 v97, 4, v96
	v_max_i32_e32 v97, 0, v97
	v_mad_u64_u32 v[98:99], s[98:99], v97, s82, v[182:183]
	global_load_dword v237, v[98:99], off offset:1024
	v_add_u32_e32 v97, 5, v96
	v_max_i32_e32 v97, 0, v97
	v_mad_u64_u32 v[98:99], s[98:99], v97, s82, v[182:183]
	global_load_dword v237, v[98:99], off offset:1024
	v_add_u32_e32 v97, 6, v96
	v_max_i32_e32 v97, 0, v97
	v_mad_u64_u32 v[98:99], s[98:99], v97, s82, v[182:183]
	global_load_dword v237, v[98:99], off offset:1024
	s_waitcnt vmcnt(18)
	v_cndmask_b32_e64 v0, v77, 0, s[20:21]
	v_cndmask_b32_e64 v77, v75, 0, s[20:21]
	v_cndmask_b32_e64 v75, v74, 0, s[20:21]
	v_cndmask_b32_e64 v86, v76, 0, s[20:21]
	v_lshlrev_b32_e32 v74, 16, v75
	s_waitcnt vmcnt(17)
	v_cndmask_b32_e64 v89, v79, 0, s[20:21]
	v_cndmask_b32_e64 v91, v78, 0, s[20:21]
	v_and_b32_e32 v75, 0xffff0000, v75
	v_lshlrev_b32_e32 v76, 16, v77
	v_and_b32_e32 v77, 0xffff0000, v77
	v_cndmask_b32_e64 v88, v81, 0, s[20:21]
	v_cndmask_b32_e64 v87, v80, 0, s[20:21]
	s_waitcnt vmcnt(16)
	v_cndmask_b32_e64 v102, v83, 0, s[20:21]
	v_cndmask_b32_e64 v98, v82, 0, s[20:21]
	s_waitcnt lgkmcnt(13)
	v_pk_fma_f32 v[74:75], v[26:27], v[74:75], v[58:59]
	v_pk_fma_f32 v[76:77], v[28:29], v[76:77], v[60:61]
	v_lshlrev_b32_e32 v78, 16, v86
	v_and_b32_e32 v79, 0xffff0000, v86
	v_lshlrev_b32_e32 v80, 16, v0
	v_and_b32_e32 v81, 0xffff0000, v0
	v_lshlrev_b32_e32 v90, 16, v91
	v_and_b32_e32 v91, 0xffff0000, v91
	v_lshlrev_b32_e32 v92, 16, v89
	v_and_b32_e32 v93, 0xffff0000, v89
	v_cndmask_b32_e64 v100, v85, 0, s[20:21]
	v_cndmask_b32_e64 v101, v84, 0, s[20:21]
	s_waitcnt lgkmcnt(12)
	v_pk_fma_f32 v[78:79], v[30:31], v[78:79], v[62:63]
	v_pk_fma_f32 v[80:81], v[32:33], v[80:81], v[64:65]
	v_pk_fma_f32 v[82:83], v[34:35], v[90:91], v[74:75]
	v_pk_fma_f32 v[84:85], v[36:37], v[92:93], v[76:77]
	v_lshlrev_b32_e32 v94, 16, v87
	v_and_b32_e32 v95, 0xffff0000, v87
	v_lshlrev_b32_e32 v96, 16, v88
	v_and_b32_e32 v97, 0xffff0000, v88
	v_lshlrev_b32_e32 v74, 16, v98
	v_and_b32_e32 v75, 0xffff0000, v98
	v_lshlrev_b32_e32 v76, 16, v102
	v_and_b32_e32 v77, 0xffff0000, v102
	v_pk_fma_f32 v[86:87], v[38:39], v[94:95], v[78:79]
	v_pk_fma_f32 v[88:89], v[40:41], v[96:97], v[80:81]
	v_pk_fma_f32 v[98:99], v[42:43], v[74:75], v[82:83]
	v_pk_fma_f32 v[84:85], v[44:45], v[76:77], v[84:85]
	v_lshlrev_b32_e32 v78, 16, v101
	v_and_b32_e32 v79, 0xffff0000, v101
	v_lshlrev_b32_e32 v80, 16, v100
	v_and_b32_e32 v81, 0xffff0000, v100
	s_waitcnt vmcnt(15)
	v_lshlrev_b32_e32 v82, 16, v70
	v_and_b32_e32 v83, 0xffff0000, v70
	v_lshlrev_b32_e32 v70, 16, v71
	v_and_b32_e32 v71, 0xffff0000, v71
	v_pk_fma_f32 v[86:87], v[46:47], v[78:79], v[86:87]
	v_pk_fma_f32 v[88:89], v[48:49], v[80:81], v[88:89]
	v_pk_fma_f32 v[100:101], v[52:53], v[70:71], v[84:85]
	v_lshlrev_b32_e32 v84, 16, v72
	v_and_b32_e32 v85, 0xffff0000, v72
	v_lshlrev_b32_e32 v72, 16, v73
	v_and_b32_e32 v73, 0xffff0000, v73
	v_pk_fma_f32 v[98:99], v[50:51], v[82:83], v[98:99]
	v_pk_fma_f32 v[102:103], v[54:55], v[84:85], v[86:87]
	v_pk_fma_f32 v[104:105], v[56:57], v[72:73], v[88:89]
	v_cvt_pk_bf16_f32 v86, v98, v99
	v_cvt_pk_bf16_f32 v87, v100, v101
	v_cvt_pk_bf16_f32 v88, v102, v103
	s_waitcnt vmcnt(14)
; #define LAS __attribute__((address_space(3)))
; __device__ __forceinline__ unsigned cvt_pk_bf16(float lo, float hi) { unsigned r; asm volatile("v_cvt_pk_bf16_f32 %0, %1, %2" : "=v"(r) : "v"(lo), "v"(hi)); return r; }
; __device__ __forceinline__ float bflo(unsigned w) { return __uint_as_float(w << 16); }
; __device__ __forceinline__ float bfhi(unsigned w) { return __uint_as_float(w & 0xffff0000u); }
; template <int PASS> __device__ __forceinline__ void lru_wave_item(LAS unsigned char* lds, LAS unsigned char* vw, int b, int c, int h, const MixP& p, int lane, float (&Hrun)[8], bool cont) {
;     ...
; #pragma unroll
;         for (int jj = 0; jj < 4; ++jj) {
;             f32x2 o[4] = {bv[0], bv[1], bv[2], bv[3]};
; #pragma unroll
;             for (int k = 0; k < 4; ++k) { const u32x4 uk = ur[jj + k];
;                 o[0] = wv[k][0] * (f32x2){bflo(uk.x), bfhi(uk.x)} + o[0]; o[1] = wv[k][1] * (f32x2){bflo(uk.y), bfhi(uk.y)} + o[1];
;                 o[2] = wv[k][2] * (f32x2){bflo(uk.z), bfhi(uk.z)} + o[2]; o[3] = wv[k][3] * (f32x2){bflo(uk.w), bfhi(uk.w)} + o[3]; }
;             { u32x4 w; w.x = cvt_pk_bf16(o[0].x, o[0].y); w.y = cvt_pk_bf16(o[1].x, o[1].y); w.z = cvt_pk_bf16(o[2].x, o[2].y); w.w = cvt_pk_bf16(o[3].x, o[3].y);
;               *(LAS u32x4*)(vw + (4 * fq + jj) * WROW + cg * 16) = w; }
;         }
;         f32x4 aR[8], aI[8];
;         bf16x8 af[4];
;         {
; #pragma unroll
;             for (int kk = 0; kk < 4; ++kk) af[kk] = *(const LAS bf16x8*)(vw + fr * WROW + kk * 64 + fq * 16);
; #pragma unroll
;             for (int n = 0; n < 8; ++n) {
;                 aR[n] = (f32x4){0.f, 0.f, 0.f, 0.f}; aI[n] = (f32x4){0.f, 0.f, 0.f, 0.f};
; #pragma unroll
;                 for (int kk = 0; kk < 4; ++kk) {
;                     const bf16x8 ba = *(const LAS bf16x8*)(lds + WA_OFF + (16 * n + fr) * WROW + kk * 64 + fq * 16);
;                     const bf16x8 bx = *(const LAS bf16x8*)(lds + WX_OFF + (16 * n + fr) * WROW + kk * 64 + fq * 16);
;                     aR[n] = __builtin_amdgcn_mfma_f32_16x16x32_bf16(af[kk], ba, aR[n], 0, 0, 0);
;                     aI[n] = __builtin_amdgcn_mfma_f32_16x16x32_bf16(af[kk], bx, aI[n], 0, 0, 0);
;                 }
;             }
	v_lshlrev_b32_e32 v98, 16, v68
	v_cvt_pk_bf16_f32 v89, v104, v105
	ds_write_b128 v229, v[86:89]
	v_pk_fma_f32 v[86:87], v[26:27], v[90:91], v[58:59]
	v_pk_fma_f32 v[88:89], v[28:29], v[92:93], v[60:61]
	v_pk_fma_f32 v[90:91], v[30:31], v[94:95], v[62:63]
	v_pk_fma_f32 v[92:93], v[32:33], v[96:97], v[64:65]
	v_pk_fma_f32 v[86:87], v[34:35], v[74:75], v[86:87]
	v_pk_fma_f32 v[88:89], v[36:37], v[76:77], v[88:89]
	v_pk_fma_f32 v[90:91], v[38:39], v[78:79], v[90:91]
	v_pk_fma_f32 v[92:93], v[40:41], v[80:81], v[92:93]
	v_pk_fma_f32 v[86:87], v[42:43], v[82:83], v[86:87]
	v_pk_fma_f32 v[88:89], v[44:45], v[70:71], v[88:89]
	v_pk_fma_f32 v[90:91], v[46:47], v[84:85], v[90:91]
	v_pk_fma_f32 v[92:93], v[48:49], v[72:73], v[92:93]
	v_lshlrev_b32_e32 v94, 16, v66
	v_and_b32_e32 v95, 0xffff0000, v66
	v_lshlrev_b32_e32 v96, 16, v67
	v_and_b32_e32 v97, 0xffff0000, v67
	v_and_b32_e32 v99, 0xffff0000, v68
	v_lshlrev_b32_e32 v100, 16, v69
	v_and_b32_e32 v101, 0xffff0000, v69
	v_pk_fma_f32 v[86:87], v[50:51], v[94:95], v[86:87]
	v_pk_fma_f32 v[88:89], v[52:53], v[96:97], v[88:89]
	v_pk_fma_f32 v[90:91], v[54:55], v[98:99], v[90:91]
	v_pk_fma_f32 v[92:93], v[56:57], v[100:101], v[92:93]
	v_cvt_pk_bf16_f32 v66, v86, v87
	v_cvt_pk_bf16_f32 v67, v88, v89
	v_cvt_pk_bf16_f32 v68, v90, v91
	s_waitcnt vmcnt(13)
	v_lshlrev_b32_e32 v86, 16, v8
	v_cvt_pk_bf16_f32 v69, v92, v93
	ds_write_b128 v229, v[66:69] offset:272
	v_pk_fma_f32 v[66:67], v[26:27], v[74:75], v[58:59]
	v_pk_fma_f32 v[68:69], v[28:29], v[76:77], v[60:61]
	v_pk_fma_f32 v[74:75], v[30:31], v[78:79], v[62:63]
	v_pk_fma_f32 v[76:77], v[32:33], v[80:81], v[64:65]
	v_pk_fma_f32 v[66:67], v[34:35], v[82:83], v[66:67]
	v_pk_fma_f32 v[68:69], v[36:37], v[70:71], v[68:69]
	v_pk_fma_f32 v[74:75], v[38:39], v[84:85], v[74:75]
	v_pk_fma_f32 v[76:77], v[40:41], v[72:73], v[76:77]
	v_pk_fma_f32 v[66:67], v[42:43], v[94:95], v[66:67]
	v_pk_fma_f32 v[68:69], v[44:45], v[96:97], v[68:69]
	v_pk_fma_f32 v[74:75], v[46:47], v[98:99], v[74:75]
	v_pk_fma_f32 v[76:77], v[48:49], v[100:101], v[76:77]
	v_lshlrev_b32_e32 v78, 16, v6
	v_and_b32_e32 v79, 0xffff0000, v6
	v_lshlrev_b32_e32 v80, 16, v7
	v_and_b32_e32 v81, 0xffff0000, v7
	v_and_b32_e32 v87, 0xffff0000, v8
	v_lshlrev_b32_e32 v88, 16, v9
	v_and_b32_e32 v89, 0xffff0000, v9
	v_pk_fma_f32 v[66:67], v[50:51], v[78:79], v[66:67]
	v_pk_fma_f32 v[68:69], v[52:53], v[80:81], v[68:69]
	v_pk_fma_f32 v[74:75], v[54:55], v[86:87], v[74:75]
	v_pk_fma_f32 v[76:77], v[56:57], v[88:89], v[76:77]
	v_cvt_pk_bf16_f32 v6, v66, v67
	v_cvt_pk_bf16_f32 v7, v68, v69
	v_cvt_pk_bf16_f32 v8, v74, v75
	v_pk_fma_f32 v[66:67], v[30:31], v[84:85], v[62:63]
	v_cvt_pk_bf16_f32 v9, v76, v77
	ds_write_b128 v229, v[6:9] offset:544
	v_pk_fma_f32 v[6:7], v[26:27], v[82:83], v[58:59]
	v_pk_fma_f32 v[8:9], v[28:29], v[70:71], v[60:61]
	v_pk_fma_f32 v[68:69], v[32:33], v[72:73], v[64:65]
	v_pk_fma_f32 v[6:7], v[34:35], v[94:95], v[6:7]
	v_pk_fma_f32 v[8:9], v[36:37], v[96:97], v[8:9]
	v_pk_fma_f32 v[66:67], v[38:39], v[98:99], v[66:67]
	v_pk_fma_f32 v[68:69], v[40:41], v[100:101], v[68:69]
	v_pk_fma_f32 v[6:7], v[42:43], v[78:79], v[6:7]
	v_pk_fma_f32 v[8:9], v[44:45], v[80:81], v[8:9]
	v_pk_fma_f32 v[70:71], v[46:47], v[86:87], v[66:67]
	v_pk_fma_f32 v[66:67], v[48:49], v[88:89], v[68:69]
	s_waitcnt vmcnt(12)
	v_lshlrev_b32_e32 v68, 16, v2
	v_and_b32_e32 v69, 0xffff0000, v2
	v_lshlrev_b32_e32 v2, 16, v3
	v_and_b32_e32 v3, 0xffff0000, v3
	v_pk_fma_f32 v[6:7], v[50:51], v[68:69], v[6:7]
	v_pk_fma_f32 v[2:3], v[52:53], v[2:3], v[8:9]
	v_lshlrev_b32_e32 v8, 16, v4
	v_and_b32_e32 v9, 0xffff0000, v4
	v_lshlrev_b32_e32 v4, 16, v5
	v_and_b32_e32 v5, 0xffff0000, v5
	v_pk_fma_f32 v[8:9], v[54:55], v[8:9], v[70:71]
	v_pk_fma_f32 v[66:67], v[56:57], v[4:5], v[66:67]
	v_cvt_pk_bf16_f32 v4, v6, v7
	v_cvt_pk_bf16_f32 v5, v2, v3
	v_cvt_pk_bf16_f32 v6, v8, v9
	v_and_or_b32 v0, v213, 64, v202
	v_cvt_pk_bf16_f32 v7, v66, v67
	ds_write_b128 v229, v[4:7] offset:816
	ds_read_b128 v[118:121], v230
	ds_read_b128 v[90:93], v230 offset:64
	ds_read_b128 v[6:9], v230 offset:128
	ds_read_b128 v[2:5], v230 offset:192
	ds_read_b128 v[66:69], v231
	ds_read_b128 v[70:73], v231 offset:34816
	ds_read_b128 v[74:77], v231 offset:64
	ds_read_b128 v[78:81], v231 offset:34880
	s_waitcnt lgkmcnt(3)
	v_mfma_f32_16x16x32_bf16 v[66:69], v[118:121], v[66:69], 0
	v_lshlrev_b32_e32 v0, 2, v0
	s_waitcnt lgkmcnt(2)
	v_mfma_f32_16x16x32_bf16 v[70:73], v[118:121], v[70:73], 0
	s_waitcnt lgkmcnt(1)
	v_mfma_f32_16x16x32_bf16 v[66:69], v[90:93], v[74:77], v[66:69]
	s_waitcnt lgkmcnt(0)
	v_mfma_f32_16x16x32_bf16 v[70:73], v[90:93], v[78:81], v[70:73]
	ds_read_b128 v[74:77], v231 offset:128
	ds_read_b128 v[78:81], v231 offset:34944
	s_waitcnt lgkmcnt(1)
	v_mfma_f32_16x16x32_bf16 v[66:69], v[6:9], v[74:77], v[66:69]
	s_waitcnt lgkmcnt(0)
	v_mfma_f32_16x16x32_bf16 v[70:73], v[6:9], v[78:81], v[70:73]
	ds_read_b128 v[74:77], v231 offset:192
	ds_read_b128 v[78:81], v231 offset:35008
	s_waitcnt lgkmcnt(1)
	v_mfma_f32_16x16x32_bf16 v[134:137], v[2:5], v[74:77], v[66:69]
	s_waitcnt lgkmcnt(0)
	v_mfma_f32_16x16x32_bf16 v[130:133], v[2:5], v[78:81], v[70:73]
	s_nop 0
	ds_read_b128 v[66:69], v231 offset:4352
	s_nop 0
	ds_read_b128 v[70:73], v231 offset:39168
	ds_read_b128 v[74:77], v231 offset:4416
	ds_read_b128 v[78:81], v231 offset:39232
	v_add_f32_e32 v134, v158, v134
	s_waitcnt lgkmcnt(3)
	v_mfma_f32_16x16x32_bf16 v[66:69], v[118:121], v[66:69], 0
	v_add_f32_e32 v135, v158, v135
	v_mul_f32_e32 v134, 0xbfb8aa3b, v134
	v_mul_f32_e32 v135, 0xbfb8aa3b, v135
	s_waitcnt lgkmcnt(2)
	v_mfma_f32_16x16x32_bf16 v[70:73], v[118:121], v[70:73], 0
	v_exp_f32_e32 v134, v134
	v_exp_f32_e32 v135, v135
	v_add_f32_e32 v130, v160, v130
	s_waitcnt lgkmcnt(1)
; #define LAS __attribute__((address_space(3)))
; template <int PASS> __device__ __forceinline__ void lru_wave_item(LAS unsigned char* lds, LAS unsigned char* vw, int b, int c, int h, const MixP& p, int lane, float (&Hrun)[8], bool cont) {
;     ...
;             for (int kk = 0; kk < 4; ++kk) af[kk] = *(const LAS bf16x8*)(vw + fr * WROW + kk * 64 + fq * 16);
; #pragma unroll
;             for (int n = 0; n < 8; ++n) {
;                 aR[n] = (f32x4){0.f, 0.f, 0.f, 0.f}; aI[n] = (f32x4){0.f, 0.f, 0.f, 0.f};
; #pragma unroll
;                 for (int kk = 0; kk < 4; ++kk) {
;                     const bf16x8 ba = *(const LAS bf16x8*)(lds + WA_OFF + (16 * n + fr) * WROW + kk * 64 + fq * 16);
;                     const bf16x8 bx = *(const LAS bf16x8*)(lds + WX_OFF + (16 * n + fr) * WROW + kk * 64 + fq * 16);
;                     aR[n] = __builtin_amdgcn_mfma_f32_16x16x32_bf16(af[kk], ba, aR[n], 0, 0, 0);
;                     aI[n] = __builtin_amdgcn_mfma_f32_16x16x32_bf16(af[kk], bx, aI[n], 0, 0, 0);
;                 }
;             }
	v_mfma_f32_16x16x32_bf16 v[66:69], v[90:93], v[74:77], v[66:69]
	v_add_f32_e32 v134, 1.0, v134
	v_add_f32_e32 v135, 1.0, v135
	v_rcp_f32_e32 v134, v134
	s_waitcnt lgkmcnt(0)
	v_mfma_f32_16x16x32_bf16 v[70:73], v[90:93], v[78:81], v[70:73]
	ds_read_b128 v[74:77], v231 offset:4480
	ds_read_b128 v[78:81], v231 offset:39296
	v_rcp_f32_e32 v135, v135
	v_mul_f32_e32 v134, v162, v134
	s_waitcnt lgkmcnt(1)
	v_mfma_f32_16x16x32_bf16 v[66:69], v[6:9], v[74:77], v[66:69]
	v_add_f32_e32 v131, v160, v131
	v_mul_f32_e32 v135, v162, v135
	v_mul_f32_e32 v130, 0xbfb8aa3b, v130
	s_waitcnt lgkmcnt(0)
	v_mfma_f32_16x16x32_bf16 v[70:73], v[6:9], v[78:81], v[70:73]
	ds_read_b128 v[74:77], v231 offset:4544
	ds_read_b128 v[78:81], v231 offset:39360
	v_exp_f32_e32 v236, v134
	v_mul_f32_e32 v131, 0xbfb8aa3b, v131
	s_waitcnt lgkmcnt(1)
	v_mfma_f32_16x16x32_bf16 v[126:129], v[2:5], v[74:77], v[66:69]
	v_exp_f32_e32 v130, v130
	v_exp_f32_e32 v131, v131
	v_fma_f32 v134, -v236, v236, 1.0
	s_waitcnt lgkmcnt(0)
	v_mfma_f32_16x16x32_bf16 v[122:125], v[2:5], v[78:81], v[70:73]
	ds_read_b128 v[66:69], v231 offset:8704
	s_nop 1
	ds_read_b128 v[70:73], v231 offset:43520
	ds_read_b128 v[74:77], v231 offset:8768
	ds_read_b128 v[78:81], v231 offset:43584
	v_add_f32_e32 v130, 1.0, v130
	s_waitcnt lgkmcnt(3)
	v_mfma_f32_16x16x32_bf16 v[66:69], v[118:121], v[66:69], 0
	v_max_f32_e32 v134, 0, v134
	v_add_f32_e32 v131, 1.0, v131
	v_rcp_f32_e32 v130, v130
	s_waitcnt lgkmcnt(2)
	v_mfma_f32_16x16x32_bf16 v[70:73], v[118:121], v[70:73], 0
	v_sqrt_f32_e32 v134, v134
	v_rcp_f32_e32 v131, v131
	v_add_f32_e32 v133, v160, v133
	s_waitcnt lgkmcnt(1)
	v_mfma_f32_16x16x32_bf16 v[66:69], v[90:93], v[74:77], v[66:69]
	v_mul_f32_e32 v133, 0xbfb8aa3b, v133
	v_exp_f32_e32 v133, v133
	v_add_f32_e32 v132, v160, v132
	s_waitcnt lgkmcnt(0)
	v_mfma_f32_16x16x32_bf16 v[70:73], v[90:93], v[78:81], v[70:73]
	ds_read_b128 v[74:77], v231 offset:8832
	ds_read_b128 v[78:81], v231 offset:43648
	v_mul_f32_e32 v132, 0xbfb8aa3b, v132
	v_exp_f32_e32 v132, v132
	s_waitcnt lgkmcnt(1)
	v_mfma_f32_16x16x32_bf16 v[66:69], v[6:9], v[74:77], v[66:69]
	v_add_f32_e32 v133, 1.0, v133
	v_add_f32_e32 v132, 1.0, v132
	v_rcp_f32_e32 v132, v132
	s_waitcnt lgkmcnt(0)
	v_mfma_f32_16x16x32_bf16 v[70:73], v[6:9], v[78:81], v[70:73]
	ds_read_b128 v[74:77], v231 offset:8896
	ds_read_b128 v[78:81], v231 offset:43712
	s_waitcnt lgkmcnt(1)
	v_mfma_f32_16x16x32_bf16 v[114:117], v[2:5], v[74:77], v[66:69]
	s_waitcnt lgkmcnt(0)
	v_mfma_f32_16x16x32_bf16 v[110:113], v[2:5], v[78:81], v[70:73]
	s_nop 0
	ds_read_b128 v[66:69], v232
	s_nop 0
	ds_read_b128 v[70:73], v232 offset:34816
	ds_read_b128 v[74:77], v232 offset:64
	ds_read_b128 v[78:81], v232 offset:34880
	s_waitcnt lgkmcnt(3)
	v_mfma_f32_16x16x32_bf16 v[66:69], v[118:121], v[66:69], 0
	s_waitcnt lgkmcnt(2)
	v_mfma_f32_16x16x32_bf16 v[70:73], v[118:121], v[70:73], 0
	s_waitcnt lgkmcnt(1)
	v_mfma_f32_16x16x32_bf16 v[66:69], v[90:93], v[74:77], v[66:69]
	s_waitcnt lgkmcnt(0)
	v_mfma_f32_16x16x32_bf16 v[70:73], v[90:93], v[78:81], v[70:73]
	ds_read_b128 v[74:77], v232 offset:128
	ds_read_b128 v[78:81], v232 offset:34944
	s_waitcnt lgkmcnt(1)
	v_mfma_f32_16x16x32_bf16 v[66:69], v[6:9], v[74:77], v[66:69]
	s_waitcnt lgkmcnt(0)
	v_mfma_f32_16x16x32_bf16 v[70:73], v[6:9], v[78:81], v[70:73]
	ds_read_b128 v[74:77], v232 offset:192
	ds_read_b128 v[78:81], v232 offset:35008
	s_waitcnt lgkmcnt(1)
	v_mfma_f32_16x16x32_bf16 v[106:109], v[2:5], v[74:77], v[66:69]
	s_waitcnt lgkmcnt(0)
	v_mfma_f32_16x16x32_bf16 v[102:105], v[2:5], v[78:81], v[70:73]
	s_nop 0
	ds_read_b128 v[66:69], v231 offset:17408
	s_nop 0
	ds_read_b128 v[70:73], v231 offset:52224
	ds_read_b128 v[74:77], v231 offset:17472
	ds_read_b128 v[78:81], v231 offset:52288
	s_waitcnt lgkmcnt(3)
	v_mfma_f32_16x16x32_bf16 v[66:69], v[118:121], v[66:69], 0
	s_waitcnt lgkmcnt(2)
	v_mfma_f32_16x16x32_bf16 v[70:73], v[118:121], v[70:73], 0
	s_waitcnt lgkmcnt(1)
	v_mfma_f32_16x16x32_bf16 v[66:69], v[90:93], v[74:77], v[66:69]
	s_waitcnt lgkmcnt(0)
	v_mfma_f32_16x16x32_bf16 v[70:73], v[90:93], v[78:81], v[70:73]
	ds_read_b128 v[74:77], v231 offset:17536
	ds_read_b128 v[78:81], v231 offset:52352
	s_waitcnt lgkmcnt(1)
	v_mfma_f32_16x16x32_bf16 v[66:69], v[6:9], v[74:77], v[66:69]
	s_waitcnt lgkmcnt(0)
	v_mfma_f32_16x16x32_bf16 v[70:73], v[6:9], v[78:81], v[70:73]
	ds_read_b128 v[74:77], v231 offset:17600
	ds_read_b128 v[78:81], v231 offset:52416
	s_waitcnt lgkmcnt(1)
	v_mfma_f32_16x16x32_bf16 v[98:101], v[2:5], v[74:77], v[66:69]
	s_waitcnt lgkmcnt(0)
	v_mfma_f32_16x16x32_bf16 v[94:97], v[2:5], v[78:81], v[70:73]
	s_nop 0
	ds_read_b128 v[66:69], v231 offset:21760
	s_nop 0
	ds_read_b128 v[70:73], v231 offset:56576
	ds_read_b128 v[74:77], v231 offset:21824
	ds_read_b128 v[78:81], v231 offset:56640
	s_waitcnt lgkmcnt(3)
	v_mfma_f32_16x16x32_bf16 v[66:69], v[118:121], v[66:69], 0
	s_waitcnt lgkmcnt(2)
	v_mfma_f32_16x16x32_bf16 v[70:73], v[118:121], v[70:73], 0
	s_waitcnt lgkmcnt(1)
	v_mfma_f32_16x16x32_bf16 v[66:69], v[90:93], v[74:77], v[66:69]
	s_waitcnt lgkmcnt(0)
	v_mfma_f32_16x16x32_bf16 v[70:73], v[90:93], v[78:81], v[70:73]
	ds_read_b128 v[74:77], v231 offset:21888
	ds_read_b128 v[78:81], v231 offset:56704
	s_waitcnt lgkmcnt(1)
	v_mfma_f32_16x16x32_bf16 v[66:69], v[6:9], v[74:77], v[66:69]
	s_waitcnt lgkmcnt(0)
	v_mfma_f32_16x16x32_bf16 v[70:73], v[6:9], v[78:81], v[70:73]
	ds_read_b128 v[74:77], v231 offset:21952
	ds_read_b128 v[78:81], v231 offset:56768
	s_waitcnt lgkmcnt(1)
	v_mfma_f32_16x16x32_bf16 v[86:89], v[2:5], v[74:77], v[66:69]
	s_waitcnt lgkmcnt(0)
; #define LAS __attribute__((address_space(3)))
; __device__ __forceinline__ float fsig2(float x) { return __builtin_amdgcn_rcpf(1.0f + __builtin_amdgcn_exp2f(-LOG2E * x)); }
; template <int PASS> __device__ __forceinline__ void lru_wave_item(LAS unsigned char* lds, LAS unsigned char* vw, int b, int c, int h, const MixP& p, int lane, float (&Hrun)[8], bool cont) {
;     ...
;             for (int kk = 0; kk < 4; ++kk) af[kk] = *(const LAS bf16x8*)(vw + fr * WROW + kk * 64 + fq * 16);
; #pragma unroll
;             for (int n = 0; n < 8; ++n) {
;                 aR[n] = (f32x4){0.f, 0.f, 0.f, 0.f}; aI[n] = (f32x4){0.f, 0.f, 0.f, 0.f};
; #pragma unroll
;                 for (int kk = 0; kk < 4; ++kk) {
;                     const bf16x8 ba = *(const LAS bf16x8*)(lds + WA_OFF + (16 * n + fr) * WROW + kk * 64 + fq * 16);
;                     const bf16x8 bx = *(const LAS bf16x8*)(lds + WX_OFF + (16 * n + fr) * WROW + kk * 64 + fq * 16);
;                     aR[n] = __builtin_amdgcn_mfma_f32_16x16x32_bf16(af[kk], ba, aR[n], 0, 0, 0);
;                     aI[n] = __builtin_amdgcn_mfma_f32_16x16x32_bf16(af[kk], bx, aI[n], 0, 0, 0);
;                 }
;             }
;         }
; #pragma unroll
;         for (int n = 0; n < 8; ++n) {
;             const f32x4 aVn = __builtin_amdgcn_mfma_f32_16x16x32_bf16(af[n >> 1], idf[n & 1], (f32x4){0.f, 0.f, 0.f, 0.f}, 0, 0, 0);
;             float av[4], bxv[4];
; #pragma unroll
;             for (int j = 0; j < 4; ++j) {
;                 const float r = fsig2(aR[n][j] + pba[n]), ig = fsig2(aI[n][j] + pbx[n]);
;                 const float a = __builtin_amdgcn_exp2f(r * pk8[n]), mult = __builtin_amdgcn_sqrtf(fmaxf(1.0f - a * a, 0.f));
;                 av[j] = a; bxv[j] = mult * ig * aVn[j];
;             }
;             const float H0 = bxv[0], H1 = av[1] * H0 + bxv[1], H2 = av[2] * H1 + bxv[2], H3 = av[3] * H2 + bxv[3];
;             const float A0 = av[0], A1 = av[1] * A0, A2 = av[2] * A1, A3 = av[3] * A2;
;             float At[4], Ht[4];
; #pragma unroll
;             for (int q = 0; q < 4; ++q) { At[q] = __shfl(A3, fr + 16 * q); Ht[q] = __shfl(H3, fr + 16 * q); }
;             const float c0 = Hrun[n], c1 = At[0] * c0 + Ht[0], c2 = At[1] * c1 + Ht[1], c3 = At[2] * c2 + Ht[2], c4 = At[3] * c3 + Ht[3];
;             Hrun[n] = c4;
;             if (PASS == 1) Arun[n] *= (At[0] * At[1]) * (At[2] * At[3]);
	v_mfma_f32_16x16x32_bf16 v[82:85], v[2:5], v[78:81], v[70:73]
	s_nop 0
	ds_read_b128 v[66:69], v231 offset:26112
	s_nop 0
	ds_read_b128 v[70:73], v231 offset:60928
	ds_read_b128 v[74:77], v231 offset:26176
	ds_read_b128 v[78:81], v231 offset:60992
	v_add_f32_e32 v86, v171, v86
	s_waitcnt lgkmcnt(3)
	v_mfma_f32_16x16x32_bf16 v[66:69], v[118:121], v[66:69], 0
	v_add_f32_e32 v87, v171, v87
	v_mul_f32_e32 v86, 0xbfb8aa3b, v86
	v_mul_f32_e32 v87, 0xbfb8aa3b, v87
	s_waitcnt lgkmcnt(2)
	v_mfma_f32_16x16x32_bf16 v[70:73], v[118:121], v[70:73], 0
	v_exp_f32_e32 v86, v86
	v_exp_f32_e32 v87, v87
	v_add_f32_e32 v82, v173, v82
	s_waitcnt lgkmcnt(1)
	v_mfma_f32_16x16x32_bf16 v[66:69], v[90:93], v[74:77], v[66:69]
	v_add_f32_e32 v86, 1.0, v86
	v_add_f32_e32 v87, 1.0, v87
	v_rcp_f32_e32 v86, v86
	s_waitcnt lgkmcnt(0)
	v_mfma_f32_16x16x32_bf16 v[70:73], v[90:93], v[78:81], v[70:73]
	ds_read_b128 v[74:77], v231 offset:26240
	ds_read_b128 v[78:81], v231 offset:61056
	v_rcp_f32_e32 v87, v87
	v_mul_f32_e32 v86, v175, v86
	s_waitcnt lgkmcnt(1)
	v_mfma_f32_16x16x32_bf16 v[66:69], v[6:9], v[74:77], v[66:69]
	ds_read_b128 v[74:77], v231 offset:26304
	ds_read_b128 v[138:141], v231 offset:61120
	v_add_f32_e32 v83, v173, v83
	v_mul_f32_e32 v87, v175, v87
	s_waitcnt lgkmcnt(2)
	v_mfma_f32_16x16x32_bf16 v[70:73], v[6:9], v[78:81], v[70:73]
	v_mul_f32_e32 v82, 0xbfb8aa3b, v82
	v_mul_f32_e32 v83, 0xbfb8aa3b, v83
	v_exp_f32_e32 v82, v82
	s_waitcnt lgkmcnt(1)
	v_mfma_f32_16x16x32_bf16 v[78:81], v[2:5], v[74:77], v[66:69]
	v_exp_f32_e32 v83, v83
	v_add_f32_e32 v85, v173, v85
	v_add_f32_e32 v82, 1.0, v82
	s_waitcnt lgkmcnt(0)
	v_mfma_f32_16x16x32_bf16 v[74:77], v[2:5], v[138:141], v[70:73]
	ds_read_b128 v[66:69], v233
	s_nop 1
	ds_read_b128 v[70:73], v233 offset:34816
	ds_read_b128 v[138:141], v233 offset:64
	ds_read_b128 v[184:187], v233 offset:34880
	v_add_f32_e32 v83, 1.0, v83
	s_waitcnt lgkmcnt(3)
	v_mfma_f32_16x16x32_bf16 v[66:69], v[118:121], v[66:69], 0
	v_rcp_f32_e32 v82, v82
	v_rcp_f32_e32 v83, v83
	v_mul_f32_e32 v85, 0xbfb8aa3b, v85
	s_waitcnt lgkmcnt(2)
	v_mfma_f32_16x16x32_bf16 v[70:73], v[118:121], v[70:73], 0
	v_exp_f32_e32 v85, v85
	s_nop 0
	v_add_f32_e32 v85, 1.0, v85
	s_waitcnt lgkmcnt(1)
	v_mfma_f32_16x16x32_bf16 v[66:69], v[90:93], v[138:141], v[66:69]
	s_waitcnt lgkmcnt(0)
	v_mfma_f32_16x16x32_bf16 v[70:73], v[90:93], v[184:187], v[70:73]
	ds_read_b128 v[138:141], v233 offset:128
	ds_read_b128 v[184:187], v233 offset:34944
	s_waitcnt lgkmcnt(1)
	v_mfma_f32_16x16x32_bf16 v[66:69], v[6:9], v[138:141], v[66:69]
	s_waitcnt lgkmcnt(0)
	v_mfma_f32_16x16x32_bf16 v[138:141], v[6:9], v[184:187], v[70:73]
	s_nop 2
	ds_read_b128 v[70:73], v233 offset:192
	ds_read_b128 v[184:187], v233 offset:35008
	s_waitcnt lgkmcnt(1)
	v_mfma_f32_16x16x32_bf16 v[70:73], v[2:5], v[70:73], v[66:69]
	s_waitcnt lgkmcnt(0)
	v_mfma_f32_16x16x32_bf16 v[66:69], v[2:5], v[184:187], v[138:141]
	v_exp_f32_e32 v186, v135
	s_nop 0
	v_fma_f32 v135, -v186, v186, 1.0
	v_max_f32_e32 v135, 0, v135
	v_sqrt_f32_e32 v135, v135
	v_mfma_f32_16x16x32_bf16 v[138:141], v[118:121], v[18:21], 0
	s_nop 1
	v_add_f32_e32 v66, v179, v66
	v_add_f32_e32 v67, v179, v67
	v_pk_mul_f32 v[130:131], v[130:131], v[134:135]
	v_add_f32_e32 v134, v158, v136
	v_mul_f32_e32 v134, 0xbfb8aa3b, v134
	v_exp_f32_e32 v134, v134
	v_pk_mul_f32 v[130:131], v[130:131], v[138:139]
	v_rcp_f32_e32 v136, v133
	v_mul_f32_e32 v66, 0xbfb8aa3b, v66
	v_add_f32_e32 v134, 1.0, v134
	v_rcp_f32_e32 v134, v134
	v_mul_f32_e32 v67, 0xbfb8aa3b, v67
	v_exp_f32_e32 v66, v66
	v_exp_f32_e32 v67, v67
	v_mul_f32_e32 v134, v162, v134
	v_exp_f32_e32 v139, v134
	v_add_f32_e32 v134, v158, v137
	v_mul_f32_e32 v134, 0xbfb8aa3b, v134
	v_exp_f32_e32 v134, v134
	v_add_f32_e32 v66, 1.0, v66
	v_add_f32_e32 v67, 1.0, v67
	v_rcp_f32_e32 v66, v66
	v_add_f32_e32 v134, 1.0, v134
	v_rcp_f32_e32 v134, v134
	v_rcp_f32_e32 v67, v67
	v_add_f32_e32 v69, v179, v69
	v_mul_f32_e32 v69, 0xbfb8aa3b, v69
	v_mul_f32_e32 v133, v162, v134
	v_exp_f32_e32 v185, v133
	v_fma_f32 v133, v186, v130, v131
	v_fma_f32 v131, -v139, v139, 1.0
	v_max_f32_e32 v131, 0, v131
	v_sqrt_f32_e32 v138, v131
	v_fma_f32 v131, -v185, v185, 1.0
	v_max_f32_e32 v131, 0, v131
	v_sqrt_f32_e32 v184, v131
	v_pk_mul_f32 v[134:135], v[132:133], v[138:139]
	v_mul_f32_e32 v131, v186, v236
	v_fmac_f32_e32 v135, v134, v140
	v_mov_b32_e32 v137, v135
	v_pk_mul_f32 v[136:137], v[136:137], v[184:185]
	v_mul_f32_e32 v132, v139, v131
	v_fmac_f32_e32 v137, v136, v141
	v_mfma_f32_16x16x32_bf16 v[138:141], v[118:121], v[22:25], 0
	v_add_f32_e32 v118, v159, v126
	v_mul_f32_e32 v118, 0xbfb8aa3b, v118
	v_exp_f32_e32 v118, v118
	v_mul_f32_e32 v134, v185, v132
	ds_bpermute_b32 v188, v0, v134
	ds_bpermute_b32 v192, v0, v137
	v_add_f32_e32 v118, 1.0, v118
	v_rcp_f32_e32 v119, v118
	v_add_f32_e32 v118, v161, v122
	v_mul_f32_e32 v118, 0xbfb8aa3b, v118
	v_exp_f32_e32 v118, v118
	v_mul_f32_e32 v119, v163, v119
	v_exp_f32_e32 v136, v119
	v_add_f32_e32 v122, v161, v125
	v_add_f32_e32 v118, 1.0, v118
	v_rcp_f32_e32 v118, v118
	v_fma_f32 v119, -v136, v136, 1.0
	v_max_f32_e32 v119, 0, v119
	v_sqrt_f32_e32 v120, v119
	v_add_f32_e32 v119, v159, v127
	v_mul_f32_e32 v119, 0xbfb8aa3b, v119
	v_exp_f32_e32 v119, v119
	v_mul_f32_e32 v122, 0xbfb8aa3b, v122
	v_exp_f32_e32 v122, v122
	ds_bpermute_b32 v190, v0, v134 offset:64
	v_add_f32_e32 v119, 1.0, v119
	v_rcp_f32_e32 v121, v119
	v_add_f32_e32 v119, v161, v123
	v_mul_f32_e32 v119, 0xbfb8aa3b, v119
	v_exp_f32_e32 v119, v119
	v_mul_f32_e32 v121, v163, v121
	v_exp_f32_e32 v185, v121
	v_add_f32_e32 v122, 1.0, v122
	v_add_f32_e32 v119, 1.0, v119
	v_rcp_f32_e32 v119, v119
	v_fma_f32 v121, -v185, v185, 1.0
; template <int PASS> __device__ __forceinline__ void lru_wave_item(LAS unsigned char* lds, LAS unsigned char* vw, int b, int c, int h, const MixP& p, int lane, float (&Hrun)[8], bool cont) {
;     ...
; #pragma unroll
;             for (int q = 0; q < 4; ++q) { At[q] = __shfl(A3, fr + 16 * q); Ht[q] = __shfl(H3, fr + 16 * q); }
;             const float c0 = Hrun[n], c1 = At[0] * c0 + Ht[0], c2 = At[1] * c1 + Ht[1], c3 = At[2] * c2 + Ht[2], c4 = At[3] * c3 + Ht[3];
;             Hrun[n] = c4;
;             if (PASS == 1) Arun[n] *= (At[0] * At[1]) * (At[2] * At[3]);
;             if (PASS == 2) {
;                 const float cin = fq == 0 ? c0 : (fq == 1 ? c1 : (fq == 2 ? c2 : c3));
;                 aR[n][0] = H0 + A0 * cin; aR[n][1] = H1 + A1 * cin; aR[n][2] = H2 + A2 * cin; aR[n][3] = H3 + A3 * cin;
;             }
	v_max_f32_e32 v121, 0, v121
	v_sqrt_f32_e32 v121, v121
	ds_bpermute_b32 v196, v0, v137 offset:64
	ds_bpermute_b32 v194, v0, v134 offset:128
	ds_bpermute_b32 v198, v0, v137 offset:128
	v_pk_mul_f32 v[118:119], v[118:119], v[120:121]
	v_add_f32_e32 v120, v159, v128
	v_mul_f32_e32 v120, 0xbfb8aa3b, v120
	v_exp_f32_e32 v120, v120
	v_pk_mul_f32 v[118:119], v[118:119], v[138:139]
	ds_bpermute_b32 v186, v0, v137 offset:192
	v_exp_f32_e32 v69, v69
	v_add_f32_e32 v120, 1.0, v120
	v_rcp_f32_e32 v121, v120
	v_add_f32_e32 v120, v161, v124
	v_mul_f32_e32 v120, 0xbfb8aa3b, v120
	v_exp_f32_e32 v120, v120
	v_mul_f32_e32 v121, v163, v121
	v_exp_f32_e32 v127, v121
	v_add_f32_e32 v121, v159, v129
	v_mul_f32_e32 v121, 0xbfb8aa3b, v121
	v_exp_f32_e32 v121, v121
	v_add_f32_e32 v120, 1.0, v120
	v_rcp_f32_e32 v120, v120
	v_rcp_f32_e32 v124, v122
	v_add_f32_e32 v121, 1.0, v121
	v_rcp_f32_e32 v121, v121
	v_add_f32_e32 v69, 1.0, v69
	ds_bpermute_b32 v184, v0, v134 offset:192
	v_mul_f32_e32 v121, v163, v121
	v_exp_f32_e32 v129, v121
	v_fma_f32 v121, v185, v118, v119
	v_fma_f32 v119, -v127, v127, 1.0
	v_max_f32_e32 v119, 0, v119
	v_sqrt_f32_e32 v126, v119
	v_fma_f32 v119, -v129, v129, 1.0
	v_max_f32_e32 v119, 0, v119
	v_sqrt_f32_e32 v128, v119
	v_pk_mul_f32 v[122:123], v[120:121], v[126:127]
	v_mul_f32_e32 v119, v185, v136
	v_fmac_f32_e32 v123, v122, v140
	v_mov_b32_e32 v125, v123
	v_pk_mul_f32 v[124:125], v[124:125], v[128:129]
	v_mul_f32_e32 v120, v127, v119
	v_fmac_f32_e32 v125, v124, v141
	v_mul_f32_e32 v122, v129, v120
	ds_bpermute_b32 v189, v0, v122
	ds_bpermute_b32 v193, v0, v125
	ds_bpermute_b32 v191, v0, v122 offset:64
	ds_bpermute_b32 v197, v0, v125 offset:64
	ds_bpermute_b32 v195, v0, v122 offset:128
	ds_bpermute_b32 v199, v0, v125 offset:128
	s_waitcnt lgkmcnt(4)
	v_pk_fma_f32 v[128:129], v[10:11], v[188:189], v[192:193]
	ds_bpermute_b32 v187, v0, v125 offset:192
	s_waitcnt lgkmcnt(3)
	v_pk_fma_f32 v[138:139], v[128:129], v[190:191], v[196:197]
	ds_bpermute_b32 v185, v0, v122 offset:192
	s_waitcnt lgkmcnt(2)
	v_pk_fma_f32 v[126:127], v[138:139], v[194:195], v[198:199]
	s_nop 0
	v_cndmask_b32_e64 v124, v126, v138, s[8:9]
	v_cndmask_b32_e64 v124, v124, v128, s[6:7]
	v_cndmask_b32_e64 v10, v124, v10, s[4:5]
	v_fmac_f32_e32 v130, v236, v10
	v_fmac_f32_e32 v133, v131, v10
	v_fmac_f32_e32 v135, v132, v10
	v_fmac_f32_e32 v137, v134, v10
	v_cndmask_b32_e64 v10, v127, v139, s[8:9]
	v_cndmask_b32_e64 v10, v10, v129, s[6:7]
	v_cndmask_b32_e64 v10, v10, v11, s[4:5]
	v_fmac_f32_e32 v118, v136, v10
	v_fmac_f32_e32 v121, v119, v10
	v_fmac_f32_e32 v123, v120, v10
	v_fmac_f32_e32 v125, v122, v10
	v_add_f32_e32 v10, v164, v114
	v_mul_f32_e32 v10, 0xbfb8aa3b, v10
	v_exp_f32_e32 v10, v10
	v_mfma_f32_16x16x32_bf16 v[138:141], v[90:93], v[18:21], 0
	v_add_f32_e32 v10, 1.0, v10
	v_rcp_f32_e32 v11, v10
	v_add_f32_e32 v10, v166, v110
	v_mul_f32_e32 v10, 0xbfb8aa3b, v10
	v_exp_f32_e32 v10, v10
	v_mul_f32_e32 v11, v168, v11
	v_exp_f32_e32 v119, v11
	v_add_f32_e32 v10, 1.0, v10
	v_rcp_f32_e32 v10, v10
	v_fma_f32 v11, -v119, v119, 1.0
	v_max_f32_e32 v11, 0, v11
	v_sqrt_f32_e32 v110, v11
	v_add_f32_e32 v11, v164, v115
	v_mul_f32_e32 v11, 0xbfb8aa3b, v11
	v_exp_f32_e32 v11, v11
	s_nop 0
	v_add_f32_e32 v11, 1.0, v11
	v_rcp_f32_e32 v114, v11
	v_add_f32_e32 v11, v166, v111
	v_mul_f32_e32 v11, 0xbfb8aa3b, v11
	v_exp_f32_e32 v11, v11
	v_mul_f32_e32 v111, v168, v114
	v_exp_f32_e32 v120, v111
	v_add_f32_e32 v11, 1.0, v11
	v_rcp_f32_e32 v11, v11
	v_fma_f32 v111, -v120, v120, 1.0
	v_max_f32_e32 v111, 0, v111
	v_sqrt_f32_e32 v111, v111
	s_nop 0
	v_pk_mul_f32 v[10:11], v[10:11], v[110:111]
	v_add_f32_e32 v110, v164, v116
	v_mul_f32_e32 v110, 0xbfb8aa3b, v110
	v_exp_f32_e32 v110, v110
	v_pk_mul_f32 v[10:11], v[10:11], v[138:139]
	v_add_f32_e32 v110, 1.0, v110
	v_rcp_f32_e32 v111, v110
	v_add_f32_e32 v110, v166, v112
	v_mul_f32_e32 v110, 0xbfb8aa3b, v110
	v_exp_f32_e32 v110, v110
	v_mul_f32_e32 v111, v168, v111
	v_exp_f32_e32 v129, v111
	v_add_f32_e32 v111, v164, v117
	v_mul_f32_e32 v111, 0xbfb8aa3b, v111
	v_exp_f32_e32 v111, v111
	v_add_f32_e32 v112, v166, v113
	v_mul_f32_e32 v112, 0xbfb8aa3b, v112
	v_exp_f32_e32 v112, v112
	v_add_f32_e32 v111, 1.0, v111
	v_rcp_f32_e32 v111, v111
	v_add_f32_e32 v110, 1.0, v110
	v_rcp_f32_e32 v110, v110
	v_add_f32_e32 v112, 1.0, v112
	v_mul_f32_e32 v111, v168, v111
	v_exp_f32_e32 v117, v111
	v_fma_f32 v111, v120, v10, v11
	v_fma_f32 v11, -v129, v129, 1.0
	v_max_f32_e32 v11, 0, v11
	v_sqrt_f32_e32 v128, v11
	v_fma_f32 v11, -v117, v117, 1.0
	v_max_f32_e32 v11, 0, v11
	v_rcp_f32_e32 v114, v112
	v_sqrt_f32_e32 v116, v11
	v_pk_mul_f32 v[112:113], v[110:111], v[128:129]
	v_mul_f32_e32 v11, v120, v119
	v_fmac_f32_e32 v113, v112, v140
	v_mov_b32_e32 v115, v113
	v_pk_mul_f32 v[114:115], v[114:115], v[116:117]
	v_mul_f32_e32 v110, v129, v11
	v_fmac_f32_e32 v115, v114, v141
	v_mfma_f32_16x16x32_bf16 v[138:141], v[90:93], v[22:25], 0
	v_add_f32_e32 v90, v165, v106
	v_mul_f32_e32 v90, 0xbfb8aa3b, v90
	v_exp_f32_e32 v90, v90
	v_mul_f32_e32 v112, v117, v110
	ds_bpermute_b32 v188, v0, v112
	ds_bpermute_b32 v190, v0, v115
	v_add_f32_e32 v90, 1.0, v90
	v_rcp_f32_e32 v91, v90
	v_add_f32_e32 v90, v167, v102
	v_mul_f32_e32 v90, 0xbfb8aa3b, v90
	v_exp_f32_e32 v90, v90
	v_mul_f32_e32 v91, v169, v91
	v_exp_f32_e32 v114, v91
	v_add_f32_e32 v102, v167, v105
	v_add_f32_e32 v90, 1.0, v90
	v_rcp_f32_e32 v90, v90
	v_fma_f32 v91, -v114, v114, 1.0
	v_max_f32_e32 v91, 0, v91
	v_sqrt_f32_e32 v92, v91
	v_add_f32_e32 v91, v165, v107
	v_mul_f32_e32 v91, 0xbfb8aa3b, v91
	v_exp_f32_e32 v91, v91
	v_mul_f32_e32 v102, 0xbfb8aa3b, v102
	v_exp_f32_e32 v102, v102
	ds_bpermute_b32 v192, v0, v112 offset:64
; __device__ __forceinline__ float fsig2(float x) { return __builtin_amdgcn_rcpf(1.0f + __builtin_amdgcn_exp2f(-LOG2E * x)); }
; template <int PASS> __device__ __forceinline__ void lru_wave_item(LAS unsigned char* lds, LAS unsigned char* vw, int b, int c, int h, const MixP& p, int lane, float (&Hrun)[8], bool cont) {
;     ...
;         for (int n = 0; n < 8; ++n) {
;             const f32x4 aVn = __builtin_amdgcn_mfma_f32_16x16x32_bf16(af[n >> 1], idf[n & 1], (f32x4){0.f, 0.f, 0.f, 0.f}, 0, 0, 0);
;             float av[4], bxv[4];
; #pragma unroll
;             for (int j = 0; j < 4; ++j) {
;                 const float r = fsig2(aR[n][j] + pba[n]), ig = fsig2(aI[n][j] + pbx[n]);
;                 const float a = __builtin_amdgcn_exp2f(r * pk8[n]), mult = __builtin_amdgcn_sqrtf(fmaxf(1.0f - a * a, 0.f));
;                 av[j] = a; bxv[j] = mult * ig * aVn[j];
;             }
;             const float H0 = bxv[0], H1 = av[1] * H0 + bxv[1], H2 = av[2] * H1 + bxv[2], H3 = av[3] * H2 + bxv[3];
;             const float A0 = av[0], A1 = av[1] * A0, A2 = av[2] * A1, A3 = av[3] * A2;
;             float At[4], Ht[4];
; #pragma unroll
;             for (int q = 0; q < 4; ++q) { At[q] = __shfl(A3, fr + 16 * q); Ht[q] = __shfl(H3, fr + 16 * q); }
;             const float c0 = Hrun[n], c1 = At[0] * c0 + Ht[0], c2 = At[1] * c1 + Ht[1], c3 = At[2] * c2 + Ht[2], c4 = At[3] * c3 + Ht[3];
;             Hrun[n] = c4;
;             if (PASS == 1) Arun[n] *= (At[0] * At[1]) * (At[2] * At[3]);
;             if (PASS == 2) {
;                 const float cin = fq == 0 ? c0 : (fq == 1 ? c1 : (fq == 2 ? c2 : c3));
;                 aR[n][0] = H0 + A0 * cin; aR[n][1] = H1 + A1 * cin; aR[n][2] = H2 + A2 * cin; aR[n][3] = H3 + A3 * cin;
;             }
	v_add_f32_e32 v91, 1.0, v91
	v_rcp_f32_e32 v93, v91
	v_add_f32_e32 v91, v167, v103
	v_mul_f32_e32 v91, 0xbfb8aa3b, v91
	v_exp_f32_e32 v91, v91
	v_mul_f32_e32 v93, v169, v93
	v_exp_f32_e32 v117, v93
	v_add_f32_e32 v102, 1.0, v102
	v_add_f32_e32 v91, 1.0, v91
	v_rcp_f32_e32 v91, v91
	v_fma_f32 v93, -v117, v117, 1.0
	v_max_f32_e32 v93, 0, v93
	v_sqrt_f32_e32 v93, v93
	ds_bpermute_b32 v194, v0, v115 offset:64
	ds_bpermute_b32 v196, v0, v112 offset:128
	ds_bpermute_b32 v198, v0, v115 offset:128
	v_pk_mul_f32 v[90:91], v[90:91], v[92:93]
	v_add_f32_e32 v92, v165, v108
	v_mul_f32_e32 v92, 0xbfb8aa3b, v92
	v_exp_f32_e32 v92, v92
	v_pk_mul_f32 v[90:91], v[90:91], v[138:139]
	ds_bpermute_b32 v128, v0, v115 offset:192
	ds_bpermute_b32 v116, v0, v112 offset:192
	v_add_f32_e32 v92, 1.0, v92
	v_rcp_f32_e32 v93, v92
	v_add_f32_e32 v92, v167, v104
	v_mul_f32_e32 v92, 0xbfb8aa3b, v92
	v_exp_f32_e32 v92, v92
	v_mul_f32_e32 v93, v169, v93
	v_exp_f32_e32 v107, v93
	v_add_f32_e32 v93, v165, v109
	v_mul_f32_e32 v93, 0xbfb8aa3b, v93
	v_exp_f32_e32 v93, v93
	v_add_f32_e32 v92, 1.0, v92
	v_rcp_f32_e32 v92, v92
	v_rcp_f32_e32 v104, v102
	v_add_f32_e32 v93, 1.0, v93
	v_rcp_f32_e32 v93, v93
	s_nop 0
	v_mul_f32_e32 v93, v169, v93
	v_exp_f32_e32 v109, v93
	v_fma_f32 v93, v117, v90, v91
	v_fma_f32 v91, -v107, v107, 1.0
	v_max_f32_e32 v91, 0, v91
	v_sqrt_f32_e32 v106, v91
	v_fma_f32 v91, -v109, v109, 1.0
	v_max_f32_e32 v91, 0, v91
	v_sqrt_f32_e32 v108, v91
	v_pk_mul_f32 v[102:103], v[92:93], v[106:107]
	v_mul_f32_e32 v91, v117, v114
	v_fmac_f32_e32 v103, v102, v140
	v_mov_b32_e32 v105, v103
	v_pk_mul_f32 v[104:105], v[104:105], v[108:109]
	v_mul_f32_e32 v92, v107, v91
	v_fmac_f32_e32 v105, v104, v141
	v_mul_f32_e32 v102, v109, v92
	ds_bpermute_b32 v189, v0, v102
	ds_bpermute_b32 v191, v0, v105
	ds_bpermute_b32 v193, v0, v102 offset:64
	ds_bpermute_b32 v195, v0, v105 offset:64
	ds_bpermute_b32 v197, v0, v102 offset:128
	ds_bpermute_b32 v199, v0, v105 offset:128
	s_waitcnt lgkmcnt(4)
	v_pk_fma_f32 v[108:109], v[12:13], v[188:189], v[190:191]
	ds_bpermute_b32 v129, v0, v105 offset:192
	s_waitcnt lgkmcnt(3)
	v_pk_fma_f32 v[138:139], v[108:109], v[192:193], v[194:195]
	ds_bpermute_b32 v117, v0, v102 offset:192
	s_waitcnt lgkmcnt(2)
	v_pk_fma_f32 v[106:107], v[138:139], v[196:197], v[198:199]
	s_nop 0
	v_cndmask_b32_e64 v104, v106, v138, s[8:9]
	v_cndmask_b32_e64 v104, v104, v108, s[6:7]
	v_cndmask_b32_e64 v12, v104, v12, s[4:5]
	v_fmac_f32_e32 v111, v11, v12
	v_cndmask_b32_e64 v11, v107, v139, s[8:9]
	v_cndmask_b32_e64 v11, v11, v109, s[6:7]
	v_cndmask_b32_e64 v11, v11, v13, s[4:5]
	v_fmac_f32_e32 v90, v114, v11
	v_fmac_f32_e32 v93, v91, v11
	v_fmac_f32_e32 v103, v92, v11
	v_fmac_f32_e32 v105, v102, v11
	v_add_f32_e32 v11, v170, v98
	v_mul_f32_e32 v11, 0xbfb8aa3b, v11
	v_exp_f32_e32 v11, v11
	v_fmac_f32_e32 v10, v119, v12
	v_fmac_f32_e32 v113, v110, v12
	v_fmac_f32_e32 v115, v112, v12
	v_add_f32_e32 v11, 1.0, v11
	v_rcp_f32_e32 v11, v11
	v_add_f32_e32 v12, v172, v94
	v_mul_f32_e32 v12, 0xbfb8aa3b, v12
	v_exp_f32_e32 v12, v12
	v_mul_f32_e32 v11, v174, v11
	v_exp_f32_e32 v11, v11
	v_mfma_f32_16x16x32_bf16 v[138:141], v[6:9], v[18:21], 0
	v_add_f32_e32 v12, 1.0, v12
	v_rcp_f32_e32 v12, v12
	v_fma_f32 v13, -v11, v11, 1.0
	v_max_f32_e32 v13, 0, v13
	v_sqrt_f32_e32 v94, v13
	v_add_f32_e32 v13, v170, v99
	v_mul_f32_e32 v13, 0xbfb8aa3b, v13
	v_exp_f32_e32 v13, v13
	v_mfma_f32_16x16x32_bf16 v[6:9], v[6:9], v[22:25], 0
	v_add_f32_e32 v13, 1.0, v13
	v_rcp_f32_e32 v91, v13
	v_add_f32_e32 v13, v172, v95
	v_mul_f32_e32 v13, 0xbfb8aa3b, v13
	v_exp_f32_e32 v13, v13
	v_mul_f32_e32 v91, v174, v91
	v_exp_f32_e32 v91, v91
	v_add_f32_e32 v13, 1.0, v13
	v_rcp_f32_e32 v13, v13
	v_fma_f32 v92, -v91, v91, 1.0
	v_max_f32_e32 v92, 0, v92
	v_sqrt_f32_e32 v95, v92
	v_add_f32_e32 v92, v170, v100
	v_mul_f32_e32 v92, 0xbfb8aa3b, v92
	v_exp_f32_e32 v92, v92
	v_pk_mul_f32 v[12:13], v[12:13], v[94:95]
	v_add_f32_e32 v95, v172, v97
	v_mul_f32_e32 v95, 0xbfb8aa3b, v95
	v_add_f32_e32 v92, 1.0, v92
	v_rcp_f32_e32 v92, v92
	v_add_f32_e32 v94, v172, v96
	v_exp_f32_e32 v95, v95
	v_mul_f32_e32 v94, 0xbfb8aa3b, v94
	v_mul_f32_e32 v92, v174, v92
	v_exp_f32_e32 v109, v92
	v_exp_f32_e32 v94, v94
	v_pk_mul_f32 v[12:13], v[12:13], v[138:139]
	v_add_f32_e32 v95, 1.0, v95
	v_rcp_f32_e32 v98, v95
	v_fma_f32 v95, v91, v12, v13
	v_fma_f32 v13, -v109, v109, 1.0
	v_add_f32_e32 v94, 1.0, v94
	v_max_f32_e32 v13, 0, v13
	v_rcp_f32_e32 v94, v94
	v_sqrt_f32_e32 v108, v13
	v_add_f32_e32 v92, v170, v101
	v_mul_f32_e32 v92, 0xbfb8aa3b, v92
	v_exp_f32_e32 v92, v92
	v_pk_mul_f32 v[96:97], v[94:95], v[108:109]
	v_exp_f32_e32 v94, v86
	v_fmac_f32_e32 v97, v96, v140
	v_exp_f32_e32 v96, v87
	v_add_f32_e32 v92, 1.0, v92
	v_fma_f32 v86, -v94, v94, 1.0
	v_max_f32_e32 v86, 0, v86
	v_fma_f32 v87, -v96, v96, 1.0
	v_max_f32_e32 v87, 0, v87
	v_sqrt_f32_e32 v86, v86
	v_sqrt_f32_e32 v87, v87
	v_rcp_f32_e32 v92, v92
	v_mov_b32_e32 v99, v97
	v_pk_mul_f32 v[82:83], v[82:83], v[86:87]
	s_nop 0
	v_pk_mul_f32 v[82:83], v[82:83], v[6:7]
	v_add_f32_e32 v6, v171, v88
	v_mul_f32_e32 v6, 0xbfb8aa3b, v6
	v_exp_f32_e32 v6, v6
	v_add_f32_e32 v7, v173, v84
	v_mul_f32_e32 v7, 0xbfb8aa3b, v7
	v_exp_f32_e32 v7, v7
	v_add_f32_e32 v6, 1.0, v6
	v_rcp_f32_e32 v6, v6
	v_mul_f32_e32 v92, v174, v92
	v_add_f32_e32 v7, 1.0, v7
	v_rcp_f32_e32 v84, v7
	v_mul_f32_e32 v6, v175, v6
	v_exp_f32_e32 v7, v6
	v_add_f32_e32 v6, v171, v89
	v_mul_f32_e32 v6, 0xbfb8aa3b, v6
	v_exp_f32_e32 v6, v6
	v_exp_f32_e32 v101, v92
	v_rcp_f32_e32 v88, v85
	v_fma_f32 v85, v96, v82, v83
	v_add_f32_e32 v6, 1.0, v6
	v_rcp_f32_e32 v6, v6
	v_fma_f32 v13, -v101, v101, 1.0
	v_max_f32_e32 v13, 0, v13
	v_sqrt_f32_e32 v100, v13
	v_mul_f32_e32 v6, v175, v6
	v_exp_f32_e32 v197, v6
	v_fma_f32 v6, -v7, v7, 1.0
	v_max_f32_e32 v6, 0, v6
	v_sqrt_f32_e32 v6, v6
	v_mul_f32_e32 v13, v91, v11
	v_mul_f32_e32 v83, v96, v94
	v_pk_mul_f32 v[98:99], v[98:99], v[100:101]
	v_pk_mul_f32 v[86:87], v[84:85], v[6:7]
	v_fma_f32 v6, -v197, v197, 1.0
	v_max_f32_e32 v6, 0, v6
	v_sqrt_f32_e32 v196, v6
	v_fmac_f32_e32 v87, v86, v8
	v_mov_b32_e32 v89, v87
	v_mul_f32_e32 v91, v109, v13
	v_pk_mul_f32 v[88:89], v[88:89], v[196:197]
	v_mul_f32_e32 v84, v7, v83
	v_fmac_f32_e32 v99, v98, v141
	v_mul_f32_e32 v92, v101, v91
	v_fmac_f32_e32 v89, v88, v9
	v_mul_f32_e32 v86, v197, v84
	ds_bpermute_b32 v138, v0, v92
	ds_bpermute_b32 v140, v0, v99
	ds_bpermute_b32 v139, v0, v86
	ds_bpermute_b32 v141, v0, v89
	ds_bpermute_b32 v188, v0, v92 offset:64
	ds_bpermute_b32 v190, v0, v99 offset:64
	ds_bpermute_b32 v189, v0, v86 offset:64
	ds_bpermute_b32 v191, v0, v89 offset:64
	ds_bpermute_b32 v192, v0, v92 offset:128
	ds_bpermute_b32 v194, v0, v99 offset:128
	ds_bpermute_b32 v193, v0, v86 offset:128
	ds_bpermute_b32 v195, v0, v89 offset:128
	s_waitcnt lgkmcnt(8)
; __device__ __forceinline__ float fsig2(float x) { return __builtin_amdgcn_rcpf(1.0f + __builtin_amdgcn_exp2f(-LOG2E * x)); }
; template <int PASS> __device__ __forceinline__ void lru_wave_item(LAS unsigned char* lds, LAS unsigned char* vw, int b, int c, int h, const MixP& p, int lane, float (&Hrun)[8], bool cont) {
;     ...
;         for (int n = 0; n < 8; ++n) {
;             const f32x4 aVn = __builtin_amdgcn_mfma_f32_16x16x32_bf16(af[n >> 1], idf[n & 1], (f32x4){0.f, 0.f, 0.f, 0.f}, 0, 0, 0);
;             float av[4], bxv[4];
; #pragma unroll
;             for (int j = 0; j < 4; ++j) {
;                 const float r = fsig2(aR[n][j] + pba[n]), ig = fsig2(aI[n][j] + pbx[n]);
;                 const float a = __builtin_amdgcn_exp2f(r * pk8[n]), mult = __builtin_amdgcn_sqrtf(fmaxf(1.0f - a * a, 0.f));
;                 av[j] = a; bxv[j] = mult * ig * aVn[j];
;             }
;             const float H0 = bxv[0], H1 = av[1] * H0 + bxv[1], H2 = av[2] * H1 + bxv[2], H3 = av[3] * H2 + bxv[3];
;             const float A0 = av[0], A1 = av[1] * A0, A2 = av[2] * A1, A3 = av[3] * A2;
;             float At[4], Ht[4];
; #pragma unroll
;             for (int q = 0; q < 4; ++q) { At[q] = __shfl(A3, fr + 16 * q); Ht[q] = __shfl(H3, fr + 16 * q); }
;             const float c0 = Hrun[n], c1 = At[0] * c0 + Ht[0], c2 = At[1] * c1 + Ht[1], c3 = At[2] * c2 + Ht[2], c4 = At[3] * c3 + Ht[3];
;             Hrun[n] = c4;
;             if (PASS == 1) Arun[n] *= (At[0] * At[1]) * (At[2] * At[3]);
;             if (PASS == 2) {
;                 const float cin = fq == 0 ? c0 : (fq == 1 ? c1 : (fq == 2 ? c2 : c3));
;                 aR[n][0] = H0 + A0 * cin; aR[n][1] = H1 + A1 * cin; aR[n][2] = H2 + A2 * cin; aR[n][3] = H3 + A3 * cin;
;             }
;         }
	v_pk_fma_f32 v[8:9], v[14:15], v[138:139], v[140:141]
	ds_bpermute_b32 v108, v0, v99 offset:192
	s_waitcnt lgkmcnt(5)
	v_pk_fma_f32 v[138:139], v[8:9], v[188:189], v[190:191]
	ds_bpermute_b32 v109, v0, v89 offset:192
	s_waitcnt lgkmcnt(2)
	v_pk_fma_f32 v[6:7], v[138:139], v[192:193], v[194:195]
	ds_bpermute_b32 v100, v0, v92 offset:192
	v_cndmask_b32_e64 v88, v6, v138, s[8:9]
	v_cndmask_b32_e64 v8, v88, v8, s[6:7]
	v_cndmask_b32_e64 v8, v8, v14, s[4:5]
	v_fmac_f32_e32 v12, v11, v8
	v_fmac_f32_e32 v95, v13, v8
	v_fmac_f32_e32 v97, v91, v8
	v_fmac_f32_e32 v99, v92, v8
	v_cndmask_b32_e64 v8, v7, v139, s[8:9]
	v_cndmask_b32_e64 v8, v8, v9, s[6:7]
	v_cndmask_b32_e64 v8, v8, v15, s[4:5]
	v_fmac_f32_e32 v82, v94, v8
	v_fmac_f32_e32 v85, v83, v8
	v_fmac_f32_e32 v87, v84, v8
	v_fmac_f32_e32 v89, v86, v8
	v_add_f32_e32 v8, v176, v78
	v_mul_f32_e32 v8, 0xbfb8aa3b, v8
	v_exp_f32_e32 v8, v8
	v_mfma_f32_16x16x32_bf16 v[138:141], v[2:5], v[18:21], 0
	ds_bpermute_b32 v101, v0, v86 offset:192
	v_add_f32_e32 v8, 1.0, v8
	v_rcp_f32_e32 v9, v8
	v_add_f32_e32 v8, v178, v74
	v_mul_f32_e32 v8, 0xbfb8aa3b, v8
	v_exp_f32_e32 v8, v8
	v_mul_f32_e32 v9, v180, v9
	v_exp_f32_e32 v11, v9
	v_mfma_f32_16x16x32_bf16 v[2:5], v[2:5], v[22:25], 0
	v_add_f32_e32 v8, 1.0, v8
	v_rcp_f32_e32 v8, v8
	v_fma_f32 v9, -v11, v11, 1.0
	v_max_f32_e32 v9, 0, v9
	v_sqrt_f32_e32 v14, v9
	v_add_f32_e32 v9, v176, v79
	v_mul_f32_e32 v9, 0xbfb8aa3b, v9
	v_exp_f32_e32 v9, v9
	s_waitcnt lgkmcnt(0)
	v_pk_fma_f32 v[6:7], v[6:7], v[100:101], v[108:109]
	v_add_f32_e32 v9, 1.0, v9
	v_rcp_f32_e32 v13, v9
	v_add_f32_e32 v9, v178, v75
	v_mul_f32_e32 v9, 0xbfb8aa3b, v9
	v_exp_f32_e32 v9, v9
	v_mul_f32_e32 v13, v180, v13
	v_exp_f32_e32 v13, v13
	v_add_f32_e32 v75, v178, v77
	v_add_f32_e32 v9, 1.0, v9
	v_rcp_f32_e32 v9, v9
	v_fma_f32 v15, -v13, v13, 1.0
	v_max_f32_e32 v15, 0, v15
	v_sqrt_f32_e32 v15, v15
	v_mul_f32_e32 v75, 0xbfb8aa3b, v75
	v_exp_f32_e32 v75, v75
	v_pk_mul_f32 v[8:9], v[8:9], v[14:15]
	s_nop 0
	v_pk_mul_f32 v[14:15], v[8:9], v[138:139]
	v_add_f32_e32 v8, v176, v80
	v_mul_f32_e32 v8, 0xbfb8aa3b, v8
	v_exp_f32_e32 v8, v8
	v_add_f32_e32 v9, v178, v76
	v_mul_f32_e32 v9, 0xbfb8aa3b, v9
	v_exp_f32_e32 v9, v9
	v_add_f32_e32 v8, 1.0, v8
	v_rcp_f32_e32 v8, v8
	v_add_f32_e32 v75, 1.0, v75
	v_add_f32_e32 v9, 1.0, v9
	v_rcp_f32_e32 v74, v9
	v_mul_f32_e32 v8, v180, v8
	v_exp_f32_e32 v9, v8
	v_add_f32_e32 v8, v176, v81
	v_mul_f32_e32 v8, 0xbfb8aa3b, v8
	v_exp_f32_e32 v8, v8
	v_rcp_f32_e32 v78, v75
	v_fma_f32 v75, v13, v14, v15
	v_mul_f32_e32 v13, v13, v11
	v_add_f32_e32 v8, 1.0, v8
	v_rcp_f32_e32 v8, v8
	v_mul_f32_e32 v15, v9, v13
	v_mul_f32_e32 v8, v180, v8
	v_exp_f32_e32 v81, v8
	v_fma_f32 v8, -v9, v9, 1.0
	v_max_f32_e32 v8, 0, v8
	v_sqrt_f32_e32 v8, v8
	s_nop 0
	v_pk_mul_f32 v[76:77], v[74:75], v[8:9]
	v_add_f32_e32 v9, v177, v70
	v_mul_f32_e32 v9, 0xbfb8aa3b, v9
	v_exp_f32_e32 v9, v9
	v_fmac_f32_e32 v77, v76, v140
	v_fma_f32 v8, -v81, v81, 1.0
	v_max_f32_e32 v8, 0, v8
	v_add_f32_e32 v9, 1.0, v9
	v_rcp_f32_e32 v9, v9
	v_sqrt_f32_e32 v80, v8
	v_mov_b32_e32 v79, v77
	v_mul_f32_e32 v74, v81, v15
	v_mul_f32_e32 v9, v181, v9
	v_exp_f32_e32 v76, v9
	v_pk_mul_f32 v[78:79], v[78:79], v[80:81]
	ds_bpermute_b32 v8, v0, v74
	v_fmac_f32_e32 v79, v78, v141
	v_fma_f32 v9, -v76, v76, 1.0
	v_max_f32_e32 v9, 0, v9
	v_sqrt_f32_e32 v70, v9
	v_add_f32_e32 v9, v177, v71
	v_mul_f32_e32 v9, 0xbfb8aa3b, v9
	v_exp_f32_e32 v9, v9
	ds_bpermute_b32 v80, v0, v79
	ds_bpermute_b32 v138, v0, v74 offset:64
	ds_bpermute_b32 v140, v0, v79 offset:64
	v_add_f32_e32 v9, 1.0, v9
	v_rcp_f32_e32 v9, v9
	ds_bpermute_b32 v188, v0, v74 offset:128
	ds_bpermute_b32 v190, v0, v79 offset:128
	ds_bpermute_b32 v192, v0, v74 offset:192
	v_mul_f32_e32 v9, v181, v9
	v_exp_f32_e32 v9, v9
	ds_bpermute_b32 v194, v0, v79 offset:192
	v_fma_f32 v71, -v9, v9, 1.0
	v_max_f32_e32 v71, 0, v71
	v_sqrt_f32_e32 v71, v71
	s_nop 0
	v_pk_mul_f32 v[66:67], v[66:67], v[70:71]
	s_nop 0
	v_pk_mul_f32 v[66:67], v[66:67], v[2:3]
	v_add_f32_e32 v2, v177, v72
	v_mul_f32_e32 v2, 0xbfb8aa3b, v2
	v_exp_f32_e32 v2, v2
	v_add_f32_e32 v3, v179, v68
	v_mul_f32_e32 v3, 0xbfb8aa3b, v3
	v_exp_f32_e32 v3, v3
	v_add_f32_e32 v2, 1.0, v2
	v_rcp_f32_e32 v2, v2
	v_rcp_f32_e32 v70, v69
	v_add_f32_e32 v3, 1.0, v3
	v_rcp_f32_e32 v68, v3
	v_mul_f32_e32 v2, v181, v2
	v_exp_f32_e32 v3, v2
	v_add_f32_e32 v2, v177, v73
	v_mul_f32_e32 v2, 0xbfb8aa3b, v2
	v_exp_f32_e32 v2, v2
	v_fma_f32 v69, v9, v66, v67
	v_mul_f32_e32 v67, v9, v76
	v_add_f32_e32 v2, 1.0, v2
	v_rcp_f32_e32 v2, v2
	s_nop 0
	v_mul_f32_e32 v2, v181, v2
	v_exp_f32_e32 v73, v2
	v_fma_f32 v2, -v3, v3, 1.0
	v_max_f32_e32 v2, 0, v2
	v_sqrt_f32_e32 v2, v2
	s_nop 0
	v_pk_mul_f32 v[196:197], v[68:69], v[2:3]
	v_fma_f32 v2, -v73, v73, 1.0
	v_max_f32_e32 v2, 0, v2
	v_sqrt_f32_e32 v72, v2
	v_fmac_f32_e32 v197, v196, v4
	v_mov_b32_e32 v71, v197
	v_mul_f32_e32 v68, v3, v67
	v_pk_mul_f32 v[70:71], v[70:71], v[72:73]
	v_pk_fma_f32 v[2:3], v[126:127], v[184:185], v[186:187]
	v_fmac_f32_e32 v71, v70, v5
	v_mul_f32_e32 v70, v73, v68
	ds_bpermute_b32 v9, v0, v70
	ds_bpermute_b32 v81, v0, v71
	ds_bpermute_b32 v139, v0, v70 offset:64
	ds_bpermute_b32 v141, v0, v71 offset:64
	ds_bpermute_b32 v189, v0, v70 offset:128
	ds_bpermute_b32 v191, v0, v71 offset:128
	s_waitcnt lgkmcnt(4)
	v_pk_fma_f32 v[72:73], v[16:17], v[8:9], v[80:81]
	ds_bpermute_b32 v193, v0, v70 offset:192
	s_waitcnt lgkmcnt(3)
	v_pk_fma_f32 v[80:81], v[72:73], v[138:139], v[140:141]
	ds_bpermute_b32 v195, v0, v71 offset:192
	s_waitcnt lgkmcnt(2)
; #define LAS __attribute__((address_space(3)))
; __device__ __forceinline__ unsigned cvt_pk_bf16(float lo, float hi) { unsigned r; asm volatile("v_cvt_pk_bf16_f32 %0, %1, %2" : "=v"(r) : "v"(lo), "v"(hi)); return r; }
; __device__ __forceinline__ float bflo(unsigned w) { return __uint_as_float(w << 16); }
; __device__ __forceinline__ float bfhi(unsigned w) { return __uint_as_float(w & 0xffff0000u); }
; template <int PASS> __device__ __forceinline__ void lru_wave_item(LAS unsigned char* lds, LAS unsigned char* vw, int b, int c, int h, const MixP& p, int lane, float (&Hrun)[8], bool cont) {
;     ...
;             const float c0 = Hrun[n], c1 = At[0] * c0 + Ht[0], c2 = At[1] * c1 + Ht[1], c3 = At[2] * c2 + Ht[2], c4 = At[3] * c3 + Ht[3];
;             Hrun[n] = c4;
;             if (PASS == 1) Arun[n] *= (At[0] * At[1]) * (At[2] * At[3]);
;             if (PASS == 2) {
;                 const float cin = fq == 0 ? c0 : (fq == 1 ? c1 : (fq == 2 ? c2 : c3));
;                 aR[n][0] = H0 + A0 * cin; aR[n][1] = H1 + A1 * cin; aR[n][2] = H2 + A2 * cin; aR[n][3] = H3 + A3 * cin;
;             }
;         }
;         if (PASS == 2) {
; #pragma unroll
;             for (int n = 0; n < 8; ++n)
; #pragma unroll
;                 for (int j = 0; j < 4; j += 2) { const unsigned w = cvt_pk_bf16(aR[n][j], aR[n][j + 1]);
;                     *(LAS unsigned short*)(vw + (4 * fq + j) * WROW + (16 * n + fr) * 2) = (unsigned short)(w & 0xffffu);
;                     *(LAS unsigned short*)(vw + (4 * fq + j + 1) * WROW + (16 * n + fr) * 2) = (unsigned short)(w >> 16); }
; #pragma unroll
;             for (int i = 0; i < 4; ++i) {
;                 const int t = fq + 4 * i; const size_t row = (size_t)(row0 + 16 * st + t);
;                 const u32x4 hh = *(const LAS u32x4*)(vw + t * WROW + cg * 16);
;                 const u32x4 g = *(const u32x4*)(p.P2 + row * P2W + h * 128 + cg * 8);
;                 const f32x4 o0 = (f32x4){bflo(hh.x) * bflo(g.x), bfhi(hh.x) * bfhi(g.x), bflo(hh.y) * bflo(g.y), bfhi(hh.y) * bfhi(g.y)};
;                 const f32x4 o1 = (f32x4){bflo(hh.z) * bflo(g.z), bfhi(hh.z) * bfhi(g.z), bflo(hh.w) * bflo(g.w), bfhi(hh.w) * bfhi(g.w)};
;                 *(u32x4*)(p.hl + row * LW + h * 128 + cg * 8) = pack8(o0, o1);
;             }
	v_pk_fma_f32 v[138:139], v[80:81], v[188:189], v[190:191]
	v_pk_fma_f32 v[4:5], v[106:107], v[116:117], v[128:129]
	v_cndmask_b32_e64 v0, v138, v80, s[8:9]
	v_cndmask_b32_e64 v0, v0, v72, s[6:7]
	v_cndmask_b32_e64 v0, v0, v16, s[4:5]
	v_fmac_f32_e32 v14, v11, v0
	v_fmac_f32_e32 v75, v13, v0
	v_fmac_f32_e32 v77, v15, v0
	v_fmac_f32_e32 v79, v74, v0
	v_cndmask_b32_e64 v0, v139, v81, s[8:9]
	v_cndmask_b32_e64 v0, v0, v73, s[6:7]
	v_cndmask_b32_e64 v0, v0, v17, s[4:5]
	v_fmac_f32_e32 v66, v76, v0
	v_fmac_f32_e32 v69, v67, v0
	v_fmac_f32_e32 v197, v68, v0
	v_fmac_f32_e32 v71, v70, v0
	v_cvt_pk_bf16_f32 v0, v130, v133
	ds_write_b16 v234, v0
	ds_write_b16_d16_hi v234, v0 offset:272
	v_cvt_pk_bf16_f32 v0, v135, v137
	ds_write_b16 v234, v0 offset:544
	ds_write_b16_d16_hi v234, v0 offset:816
	v_cvt_pk_bf16_f32 v0, v118, v121
	ds_write_b16 v234, v0 offset:32
	ds_write_b16_d16_hi v234, v0 offset:304
	v_cvt_pk_bf16_f32 v0, v123, v125
	ds_write_b16 v234, v0 offset:576
	ds_write_b16_d16_hi v234, v0 offset:848
	v_cvt_pk_bf16_f32 v0, v10, v111
	ds_write_b16 v234, v0 offset:64
	ds_write_b16_d16_hi v234, v0 offset:336
	v_cvt_pk_bf16_f32 v0, v113, v115
	ds_write_b16 v234, v0 offset:608
	ds_write_b16_d16_hi v234, v0 offset:880
	v_cvt_pk_bf16_f32 v0, v90, v93
	ds_write_b16 v234, v0 offset:96
	ds_write_b16_d16_hi v234, v0 offset:368
	v_cvt_pk_bf16_f32 v0, v103, v105
	ds_write_b16 v234, v0 offset:640
	ds_write_b16_d16_hi v234, v0 offset:912
	v_cvt_pk_bf16_f32 v0, v12, v95
	ds_write_b16 v234, v0 offset:128
	ds_write_b16_d16_hi v234, v0 offset:400
	v_cvt_pk_bf16_f32 v0, v97, v99
	ds_write_b16 v234, v0 offset:672
	ds_write_b16_d16_hi v234, v0 offset:944
	v_cvt_pk_bf16_f32 v0, v82, v85
	ds_write_b16 v234, v0 offset:160
	ds_write_b16_d16_hi v234, v0 offset:432
	v_cvt_pk_bf16_f32 v0, v87, v89
	ds_write_b16 v234, v0 offset:704
	ds_write_b16_d16_hi v234, v0 offset:976
	v_cvt_pk_bf16_f32 v0, v14, v75
	ds_write_b16 v234, v0 offset:192
	ds_write_b16_d16_hi v234, v0 offset:464
	v_cvt_pk_bf16_f32 v0, v77, v79
	ds_write_b16 v234, v0 offset:736
	ds_write_b16_d16_hi v234, v0 offset:1008
	v_cvt_pk_bf16_f32 v0, v66, v69
	ds_write_b16 v234, v0 offset:224
	ds_write_b16_d16_hi v234, v0 offset:496
	v_cvt_pk_bf16_f32 v0, v197, v71
	ds_write_b16 v234, v0 offset:768
	ds_write_b16_d16_hi v234, v0 offset:1040
	v_or_b32_e32 v0, s19, v203
	ds_read_b128 v[10:13], v235
	s_waitcnt lgkmcnt(14)
	v_pk_fma_f32 v[8:9], v[138:139], v[192:193], v[194:195]
	s_waitcnt lgkmcnt(0)
	v_lshlrev_b32_e32 v67, 16, v10
	v_and_b32_e32 v10, 0xffff0000, v10
	s_waitcnt vmcnt(11)
	v_lshlrev_b32_e32 v66, 16, v240
	v_and_b32_e32 v240, 0xffff0000, v240
	v_mul_f32_e32 v66, v66, v67
	v_mul_f32_e32 v10, v240, v10
	v_lshlrev_b32_e32 v240, 16, v241
	v_lshlrev_b32_e32 v67, 16, v11
	v_and_b32_e32 v241, 0xffff0000, v241
	v_and_b32_e32 v11, 0xffff0000, v11
	v_mul_f32_e32 v240, v240, v67
	v_mul_f32_e32 v11, v241, v11
	v_lshlrev_b32_e32 v241, 16, v242
	v_lshlrev_b32_e32 v67, 16, v12
	v_and_b32_e32 v242, 0xffff0000, v242
	v_and_b32_e32 v12, 0xffff0000, v12
	v_mul_f32_e32 v241, v241, v67
	v_mul_f32_e32 v12, v242, v12
	v_lshlrev_b32_e32 v242, 16, v243
	v_lshlrev_b32_e32 v67, 16, v13
	v_and_b32_e32 v243, 0xffff0000, v243
	v_and_b32_e32 v13, 0xffff0000, v13
	v_mul_f32_e32 v13, v243, v13
	v_cvt_pk_bf16_f32 v10, v66, v10
	v_cvt_pk_bf16_f32 v11, v240, v11
	v_cvt_pk_bf16_f32 v12, v241, v12
	v_mad_i64_i32 v[14:15], s[20:21], v0, s40, v[154:155]
	v_or_b32_e32 v0, s19, v225
	v_mul_f32_e32 v242, v242, v67
	v_cvt_pk_bf16_f32 v13, v242, v13
	global_store_dwordx4 v[14:15], v[10:13], off
	ds_read_b128 v[10:13], v235 offset:1088
	s_waitcnt lgkmcnt(0)
; #define LAS __attribute__((address_space(3)))
; __device__ __forceinline__ float bflo(unsigned w) { return __uint_as_float(w << 16); }
; __device__ __forceinline__ float bfhi(unsigned w) { return __uint_as_float(w & 0xffff0000u); }
; __device__ __forceinline__ u32x4 pack8(const f32x4 a, const f32x4 b) { u32x4 w; w.x = cvt_pk_bf16(a[0], a[1]); w.y = cvt_pk_bf16(a[2], a[3]); w.z = cvt_pk_bf16(b[0], b[1]); w.w = cvt_pk_bf16(b[2], b[3]); return w; }
; template <int PASS> __device__ __forceinline__ void lru_wave_item(LAS unsigned char* lds, LAS unsigned char* vw, int b, int c, int h, const MixP& p, int lane, float (&Hrun)[8], bool cont) {
;     ...
;             for (int i = 0; i < 4; ++i) {
;                 const int t = fq + 4 * i; const size_t row = (size_t)(row0 + 16 * st + t);
;                 const u32x4 hh = *(const LAS u32x4*)(vw + t * WROW + cg * 16);
;                 const u32x4 g = *(const u32x4*)(p.P2 + row * P2W + h * 128 + cg * 8);
;                 const f32x4 o0 = (f32x4){bflo(hh.x) * bflo(g.x), bfhi(hh.x) * bfhi(g.x), bflo(hh.y) * bflo(g.y), bfhi(hh.y) * bfhi(g.y)};
;                 const f32x4 o1 = (f32x4){bflo(hh.z) * bflo(g.z), bfhi(hh.z) * bfhi(g.z), bflo(hh.w) * bflo(g.w), bfhi(hh.w) * bfhi(g.w)};
;                 *(u32x4*)(p.hl + row * LW + h * 128 + cg * 8) = pack8(o0, o1);
;             }
	v_lshlrev_b32_e32 v66, 16, v10
	v_and_b32_e32 v10, 0xffff0000, v10
	s_waitcnt vmcnt(11)
	v_lshlrev_b32_e32 v67, 16, v244
	v_and_b32_e32 v244, 0xffff0000, v244
	v_mul_f32_e32 v66, v67, v66
	v_mul_f32_e32 v10, v244, v10
	v_lshlrev_b32_e32 v244, 16, v11
	v_lshlrev_b32_e32 v67, 16, v245
	v_and_b32_e32 v245, 0xffff0000, v245
	v_and_b32_e32 v11, 0xffff0000, v11
	v_mul_f32_e32 v244, v67, v244
	v_mul_f32_e32 v11, v245, v11
	v_lshlrev_b32_e32 v245, 16, v12
	v_lshlrev_b32_e32 v67, 16, v246
	v_and_b32_e32 v246, 0xffff0000, v246
	v_and_b32_e32 v12, 0xffff0000, v12
	v_mul_f32_e32 v245, v67, v245
	v_mul_f32_e32 v12, v246, v12
	v_lshlrev_b32_e32 v246, 16, v13
	v_lshlrev_b32_e32 v67, 16, v247
	v_and_b32_e32 v247, 0xffff0000, v247
	v_and_b32_e32 v13, 0xffff0000, v13
	v_mul_f32_e32 v13, v247, v13
	v_cvt_pk_bf16_f32 v10, v66, v10
	v_cvt_pk_bf16_f32 v11, v244, v11
	v_cvt_pk_bf16_f32 v12, v245, v12
	v_mad_i64_i32 v[14:15], s[20:21], v0, s40, v[154:155]
	v_or_b32_e32 v0, s19, v226
	v_mul_f32_e32 v246, v67, v246
	v_cvt_pk_bf16_f32 v13, v246, v13
	global_store_dwordx4 v[14:15], v[10:13], off
	ds_read_b128 v[10:13], v235 offset:2176
	s_waitcnt lgkmcnt(0)
	v_lshlrev_b32_e32 v66, 16, v10
	v_and_b32_e32 v10, 0xffff0000, v10
	s_waitcnt vmcnt(11)
	v_lshlrev_b32_e32 v67, 16, v248
	v_and_b32_e32 v248, 0xffff0000, v248
	v_mul_f32_e32 v66, v67, v66
	v_mul_f32_e32 v10, v248, v10
	v_lshlrev_b32_e32 v248, 16, v11
	v_lshlrev_b32_e32 v67, 16, v249
	v_and_b32_e32 v249, 0xffff0000, v249
	v_and_b32_e32 v11, 0xffff0000, v11
	v_mul_f32_e32 v248, v67, v248
	v_mul_f32_e32 v11, v249, v11
	v_lshlrev_b32_e32 v249, 16, v12
	v_lshlrev_b32_e32 v67, 16, v250
	v_and_b32_e32 v250, 0xffff0000, v250
	v_and_b32_e32 v12, 0xffff0000, v12
	v_mul_f32_e32 v249, v67, v249
	v_mul_f32_e32 v12, v250, v12
	v_lshlrev_b32_e32 v250, 16, v13
	v_lshlrev_b32_e32 v67, 16, v251
	v_and_b32_e32 v251, 0xffff0000, v251
	v_and_b32_e32 v13, 0xffff0000, v13
	v_mul_f32_e32 v13, v251, v13
	v_cvt_pk_bf16_f32 v10, v66, v10
	v_cvt_pk_bf16_f32 v11, v248, v11
	v_cvt_pk_bf16_f32 v12, v249, v12
	v_mad_i64_i32 v[14:15], s[20:21], v0, s40, v[154:155]
	v_or_b32_e32 v0, s19, v227
	v_mul_f32_e32 v250, v67, v250
	v_cvt_pk_bf16_f32 v13, v250, v13
	global_store_dwordx4 v[14:15], v[10:13], off
	ds_read_b128 v[10:13], v235 offset:3264
	s_mov_b32 s19, 16
	s_waitcnt lgkmcnt(0)
	v_lshlrev_b32_e32 v66, 16, v10
	v_and_b32_e32 v10, 0xffff0000, v10
	s_waitcnt vmcnt(10)
	v_lshlrev_b32_e32 v67, 16, v206
	v_and_b32_e32 v206, 0xffff0000, v206
	v_mul_f32_e32 v66, v67, v66
	v_mul_f32_e32 v10, v206, v10
	v_lshlrev_b32_e32 v206, 16, v11
	v_lshlrev_b32_e32 v67, 16, v207
	v_and_b32_e32 v207, 0xffff0000, v207
	v_and_b32_e32 v11, 0xffff0000, v11
	v_mul_f32_e32 v206, v67, v206
	v_mul_f32_e32 v11, v207, v11
	v_lshlrev_b32_e32 v207, 16, v12
	v_lshlrev_b32_e32 v67, 16, v210
	v_and_b32_e32 v210, 0xffff0000, v210
	v_and_b32_e32 v12, 0xffff0000, v12
	v_mul_f32_e32 v207, v67, v207
	v_mul_f32_e32 v12, v210, v12
	v_lshlrev_b32_e32 v210, 16, v13
	v_lshlrev_b32_e32 v67, 16, v211
	v_and_b32_e32 v211, 0xffff0000, v211
	v_and_b32_e32 v13, 0xffff0000, v13
	v_mul_f32_e32 v13, v211, v13
	v_mul_f32_e32 v210, v67, v210
	v_cvt_pk_bf16_f32 v10, v66, v10
	v_cvt_pk_bf16_f32 v11, v206, v11
	v_cvt_pk_bf16_f32 v12, v207, v12
	v_cvt_pk_bf16_f32 v13, v210, v13
	v_mad_i64_i32 v[14:15], s[20:21], v0, s40, v[154:155]
	global_store_dwordx4 v[14:15], v[10:13], off
	v_mov_b64_e32 v[16:17], v[8:9]
	v_mov_b64_e32 v[14:15], v[6:7]
	v_mov_b64_e32 v[12:13], v[4:5]
	v_mov_b64_e32 v[10:11], v[2:3]
	s_cbranch_vccnz .LBB0_818
	s_add_i32 s1, s1, 1
	s_cmp_ge_i32 s1, s10
	s_cbranch_scc0 .LBB0_811
	s_branch .LBB0_797
